# adds: P3 gate-epilogue constants prefetched before K loop; attention K/V staging loads use scalar tile base (no per-tile VALU address math); negm copy removed
# speedup vs baseline: 1.0273x; 1.0100x over previous
;     __device__ __forceinline__ void operator()(const Acc& acc, const Unit& u, int wr, int wc, int fr, int fq) const {
;         const int blk = u.pn >> 1, dir = u.pn & 1, rowt = u.pm * 256 + wr * 64 + fr, j0 = wc * 32 + 8 * fq, ch = blk * 128 + j0;
;         const float* pbr = br + (dir * 4 + blk) * 128; const float* pbi = bi + (dir * 4 + blk) * 128; const float* psp = sp8 + dir * 512 + blk * 128;
;         u32x4 xw[8];
; #pragma unroll
;         for (int i = 0; i < 8; ++i) xw[i] = *(const u32x4*)(XC + (unsigned)((rowt + (i >> 2) * 128 + (i & 3) * 16) * 512 + ch));
;         f32x4 cbr[2], cbi[2], csp[2];
; #pragma unroll
;         for (int h = 0; h < 2; ++h) { cbr[h] = *(const f32x4*)(pbr + (unsigned)(j0 + 4 * h)); cbi[h] = *(const f32x4*)(pbi + (unsigned)(j0 + 4 * h)); csp[h] = *(const f32x4*)(psp + (unsigned)(j0 + 4 * h)); }
.LBB0_538:
	s_ashr_i32 s48, s42, 1
	s_ashr_i32 s45, s44, 31
	s_ashr_i32 s49, s48, 31
	s_lshl_b64 s[46:47], s[44:45], 18
	s_lshl_b64 s[48:49], s[48:49], 8
	s_add_u32 s5, s26, s48
	s_addc_u32 s43, s27, s49
	s_add_u32 s46, s5, s46
	s_addc_u32 s47, s43, s47
	s_ashr_i32 s43, s42, 31
	s_lshl_b64 s[48:49], s[42:43], 16
	s_add_u32 s48, s84, s48
	s_addc_u32 s49, s85, s49
	s_andn2_b64 vcc, exec, s[34:35]
	s_waitcnt lgkmcnt(0)
	s_cbranch_vccnz .Lzstub_3
	s_and_b32 s100, s50, 1
	s_lshl_b32 s98, s50, 6
	s_and_b32 s98, s98, 0xffffff80
	s_lshl_b32 s101, s100, 9
	s_add_i32 s101, s101, s98
	s_lshl_b32 s99, s100, 11
	s_lshl_b32 s98, s98, 2
	s_add_i32 s98, s98, s99
	s_lshl_b32 s101, s101, 2
	v_readlane_b32 s100, v252, 34
	s_nop 0
	s_add_u32 s98, s100, s98
	v_readlane_b32 s100, v252, 35
	s_nop 0
	s_addc_u32 s99, s100, 0
	s_mov_b32 s100, s101
	s_mov_b32 s101, 0
	v_lshl_add_u64 v[244:245], v[196:197], 0, s[100:101]
	v_lshlrev_b32_e32 v219, 2, v194
	global_load_dwordx4 v[240:243], v[244:245], off
	global_load_dwordx4 v[244:247], v[244:245], off offset:16
	global_load_dwordx4 v[248:251], v219, s[98:99]
	global_load_dword v253, v219, s[98:99] offset:16
	global_load_dword v254, v219, s[98:99] offset:20
	global_load_dword v255, v219, s[98:99] offset:24
	global_load_dword v219, v219, s[98:99] offset:28
	s_and_b64 s[76:77], s[0:1], exec
	s_cselect_b32 s5, s47, s55
	s_cselect_b32 s43, s46, s54
	s_cselect_b32 s45, s49, s53
	s_cselect_b32 s73, s48, s52
	s_add_u32 s75, s52, 0x100
	s_addc_u32 s76, s53, 0
	s_add_u32 s52, s54, 0x80
	v_mov_b32_e32 v0, 0
	s_addc_u32 s53, s55, 0
	s_mov_b32 s54, 0
	v_mov_b32_e32 v1, v0
	v_mov_b32_e32 v2, v0
	v_mov_b32_e32 v3, v0
	v_mov_b32_e32 v4, v0
	v_mov_b32_e32 v5, v0
	v_mov_b32_e32 v6, v0
	v_mov_b32_e32 v7, v0
	v_mov_b32_e32 v20, v0
	v_mov_b32_e32 v21, v0
	v_mov_b32_e32 v22, v0
	v_mov_b32_e32 v23, v0
	v_mov_b32_e32 v16, v0
	v_mov_b32_e32 v17, v0
	v_mov_b32_e32 v18, v0
	v_mov_b32_e32 v19, v0
	v_mov_b32_e32 v36, v0
	v_mov_b32_e32 v37, v0
	v_mov_b32_e32 v38, v0
	v_mov_b32_e32 v39, v0
	v_mov_b32_e32 v32, v0
	v_mov_b32_e32 v33, v0
	v_mov_b32_e32 v34, v0
	v_mov_b32_e32 v35, v0
	v_mov_b32_e32 v60, v0
	v_mov_b32_e32 v61, v0
	v_mov_b32_e32 v62, v0
	v_mov_b32_e32 v63, v0
	v_mov_b32_e32 v48, v0
	v_mov_b32_e32 v49, v0
	v_mov_b32_e32 v50, v0
	v_mov_b32_e32 v51, v0
	v_mov_b32_e32 v8, v0
	v_mov_b32_e32 v9, v0
	v_mov_b32_e32 v10, v0
	v_mov_b32_e32 v11, v0
	v_mov_b32_e32 v12, v0
	v_mov_b32_e32 v13, v0
	v_mov_b32_e32 v14, v0
	v_mov_b32_e32 v15, v0
	v_mov_b32_e32 v24, v0
	v_mov_b32_e32 v25, v0
	v_mov_b32_e32 v26, v0
	v_mov_b32_e32 v27, v0
	v_mov_b32_e32 v28, v0
	v_mov_b32_e32 v29, v0
	v_mov_b32_e32 v30, v0
	v_mov_b32_e32 v31, v0
	v_mov_b32_e32 v40, v0
	v_mov_b32_e32 v41, v0
	v_mov_b32_e32 v42, v0
	v_mov_b32_e32 v43, v0
	v_mov_b32_e32 v44, v0
	v_mov_b32_e32 v45, v0
	v_mov_b32_e32 v46, v0
	v_mov_b32_e32 v47, v0
	v_mov_b32_e32 v68, v0
	v_mov_b32_e32 v69, v0
	v_mov_b32_e32 v70, v0
	v_mov_b32_e32 v71, v0
	v_mov_b32_e32 v80, v0
	v_mov_b32_e32 v81, v0
	v_mov_b32_e32 v82, v0
	v_mov_b32_e32 v83, v0
	v_mov_b32_e32 v100, v0
	v_mov_b32_e32 v101, v0
	v_mov_b32_e32 v102, v0
	v_mov_b32_e32 v103, v0
	v_mov_b32_e32 v92, v0
	v_mov_b32_e32 v93, v0
	v_mov_b32_e32 v94, v0
	v_mov_b32_e32 v95, v0
	v_mov_b32_e32 v120, v0
	v_mov_b32_e32 v121, v0
	v_mov_b32_e32 v122, v0
	v_mov_b32_e32 v123, v0
	v_mov_b32_e32 v112, v0
	v_mov_b32_e32 v113, v0
	v_mov_b32_e32 v114, v0
	v_mov_b32_e32 v115, v0
	v_mov_b32_e32 v140, v0
	v_mov_b32_e32 v141, v0
	v_mov_b32_e32 v142, v0
	v_mov_b32_e32 v143, v0
	v_mov_b32_e32 v132, v0
	v_mov_b32_e32 v133, v0
	v_mov_b32_e32 v134, v0
	v_mov_b32_e32 v135, v0
	v_mov_b32_e32 v160, v0
	v_mov_b32_e32 v161, v0
	v_mov_b32_e32 v162, v0
	v_mov_b32_e32 v163, v0
	v_mov_b32_e32 v156, v0
	v_mov_b32_e32 v157, v0
	v_mov_b32_e32 v158, v0
	v_mov_b32_e32 v159, v0
	v_mov_b32_e32 v104, v0
	v_mov_b32_e32 v105, v0
	v_mov_b32_e32 v106, v0
	v_mov_b32_e32 v107, v0
	v_mov_b32_e32 v108, v0
	v_mov_b32_e32 v109, v0
	v_mov_b32_e32 v110, v0
	v_mov_b32_e32 v111, v0
	v_mov_b32_e32 v124, v0
	v_mov_b32_e32 v125, v0
	v_mov_b32_e32 v126, v0
	v_mov_b32_e32 v127, v0
	v_mov_b32_e32 v128, v0
	v_mov_b32_e32 v129, v0
	v_mov_b32_e32 v130, v0
	v_mov_b32_e32 v131, v0
	v_mov_b32_e32 v144, v0
	v_mov_b32_e32 v145, v0
	v_mov_b32_e32 v146, v0
	v_mov_b32_e32 v147, v0
	v_mov_b32_e32 v148, v0
	v_mov_b32_e32 v149, v0
	v_mov_b32_e32 v150, v0
	v_mov_b32_e32 v151, v0
	v_mov_b32_e32 v164, v0
	v_mov_b32_e32 v165, v0
	v_mov_b32_e32 v166, v0
	v_mov_b32_e32 v167, v0
	v_mov_b32_e32 v168, v0
	v_mov_b32_e32 v169, v0
	v_mov_b32_e32 v170, v0
	v_mov_b32_e32 v171, v0

; __device__ __forceinline__ float fsigmoid(float x) { return __builtin_amdgcn_rcpf(1.0f + __builtin_amdgcn_exp2f(-x * LOG2E)); }
; __device__ __forceinline__ void unpack8(u32x4 w, f32x4& a, f32x4& b) { a = (f32x4){bf_lo(w.x), bf_hi(w.x), bf_lo(w.y), bf_hi(w.y)}; b = (f32x4){bf_lo(w.z), bf_hi(w.z), bf_lo(w.w), bf_hi(w.w)}; }
; __device__ __forceinline__ unsigned pack_h2(float lo, float hi) { const __half2 h = __floats2half2_rn(lo, hi); return *(const unsigned*)&h; }
;     __device__ __forceinline__ void operator()(const Acc& acc, const Unit& u, int wr, int wc, int fr, int fq) const {
;     ...
;                 f32x4 x0, x1; unpack8(xw[ai * 4 + m], x0, x1);
;                 u32x4 o0, o1;
; #pragma unroll
;                 for (int h = 0; h < 2; ++h) { const f32x4 ar = acc[ai][0][m][h] + cbr[h], aiq = acc[ai][1][m][h] + cbi[h], sp = csp[h], xx = h ? x1 : x0; u32x4 o;
; #pragma unroll
;                     for (int e = 0; e < 4; ++e) { const float rr = fsigmoid(ar[e]), ii = fsigmoid(aiq[e]); const float la = -rr * sp[e], y = 2.0f * la;
;                         float m2 = -y * (1.0f + y * (0.5f + y * (0.16666667f + y * (0.041666668f + y * 0.0083333338f))));
;                         if (__builtin_expect(__any(y < -0.25f), 0)) m2 = (y < -0.25f) ? 1.0f - __builtin_amdgcn_exp2f(y * LOG2E) : m2;
;                         const float uu = ii * xx[e] * __builtin_amdgcn_sqrtf(m2); o[e] = pack_h2(la * LOG2E, uu); }
.LBB0_544:
	s_and_b32 s5, s50, 1
	v_lshl_add_u32 v213, s4, 8, v195
	s_lshl_b32 s4, s50, 6
	s_and_b32 s52, s4, 0xffffff80
	s_lshl_b32 s4, s5, 9
	s_add_i32 s54, s4, s52
	s_ashr_i32 s55, s54, 31
	s_ashr_i32 s53, s52, 31
	s_lshl_b32 s4, s5, 11
	v_or_b32_e32 v214, s52, v194
	v_lshlrev_b32_e32 v58, 9, v213
	s_add_u32 s4, s68, s4
	v_add_u32_e32 v192, v58, v214
	v_add_u32_e32 v59, 0x2000, v214
	s_addc_u32 s43, s69, 0
	s_lshl_b64 s[52:53], s[52:53], 2
	v_lshl_add_u64 v[52:53], v[192:193], 1, s[26:27]
	v_add_u32_e32 v192, v59, v58
	v_add_u32_e32 v64, 0x4000, v214
	s_add_u32 s52, s4, s52
	v_lshl_add_u64 v[54:55], v[192:193], 1, s[26:27]
	v_add_u32_e32 v192, v64, v58
	v_add_u32_e32 v65, 0x6000, v214
	s_addc_u32 s53, s43, s53
	s_lshl_b64 s[54:55], s[54:55], 2
	global_load_dwordx4 v[180:183], v[52:53], off
	global_load_dwordx4 v[176:179], v[54:55], off
	v_lshl_add_u64 v[52:53], v[192:193], 1, s[26:27]
	v_add_u32_e32 v192, v65, v58
	v_lshl_add_u64 v[56:57], v[196:197], 0, s[54:55]
	v_lshl_add_u64 v[54:55], v[192:193], 1, s[26:27]
	global_load_dwordx4 v[172:175], v[52:53], off
	global_load_dwordx4 v[152:155], v[54:55], off
	v_add_u32_e32 v56, 0x10000, v58
	v_add_u32_e32 v192, v56, v214
	v_lshl_add_u64 v[52:53], v[192:193], 1, s[26:27]
	v_add_u32_e32 v192, v56, v59
	v_lshlrev_b32_e32 v57, 2, v194
	v_lshl_add_u64 v[54:55], v[192:193], 1, s[26:27]
	global_load_dwordx4 v[136:139], v[52:53], off
	global_load_dwordx4 v[116:119], v[54:55], off
	v_add_u32_e32 v192, v56, v64
	v_lshl_add_u64 v[52:53], v[192:193], 1, s[26:27]
	v_add_u32_e32 v192, v56, v65
	v_lshl_add_u64 v[54:55], v[192:193], 1, s[26:27]
	v_lshl_add_u64 v[64:65], v[198:199], 0, s[54:55]
	global_load_dwordx4 v[56:59], v[64:65], off offset:16
	s_nop 0
	global_load_dwordx4 v[64:67], v[64:65], off
	s_nop 0
	global_load_dwordx4 v[96:99], v[52:53], off
	s_nop 0
	global_load_dwordx4 v[52:55], v[54:55], off
	s_waitcnt vmcnt(10)
	v_add_f32_e32 v168, v168, v240
	v_mul_f32_e32 v168, 0xbfb8aa3b, v168
	v_exp_f32_e32 v168, v168
	s_nop 0
	v_add_f32_e32 v168, 1.0, v168
	v_rcp_f32_e64 v168, -v168
	s_nop 0
	v_mul_f32_e32 v168, v248, v168
	v_add_f32_e32 v215, v168, v168
	v_fmamk_f32 v192, v215, 0x3c088889, v212
	v_fmaak_f32 v192, v215, v192, 0x3e2aaaab
	v_fma_f32 v192, v215, v192, 0.5
	v_fma_f32 v192, v215, v192, 1.0
	v_cmp_gt_f32_e32 vcc, s72, v215
	v_mul_f32_e64 v192, v192, -v215
	s_cbranch_vccnz .LBB0_611
.LBB0_545:
	v_add_f32_e32 v224, v169, v241
	v_add_f32_e32 v225, v170, v242
	v_add_f32_e32 v226, v171, v243
	v_add_f32_e32 v227, v164, v244
	v_add_f32_e32 v228, v165, v245
	v_add_f32_e32 v229, v166, v246
	v_add_f32_e32 v230, v167, v247
	v_mul_f32_e32 v224, 0xbfb8aa3b, v224
	v_mul_f32_e32 v225, 0xbfb8aa3b, v225
	v_mul_f32_e32 v226, 0xbfb8aa3b, v226
	v_mul_f32_e32 v227, 0xbfb8aa3b, v227
	v_mul_f32_e32 v228, 0xbfb8aa3b, v228
	v_mul_f32_e32 v229, 0xbfb8aa3b, v229
	v_mul_f32_e32 v230, 0xbfb8aa3b, v230
	v_exp_f32_e32 v224, v224
	v_exp_f32_e32 v225, v225
	v_exp_f32_e32 v226, v226
	v_exp_f32_e32 v227, v227
	v_exp_f32_e32 v228, v228
	v_exp_f32_e32 v229, v229
	v_exp_f32_e32 v230, v230
	v_add_f32_e32 v224, 1.0, v224
	v_add_f32_e32 v225, 1.0, v225
	v_add_f32_e32 v226, 1.0, v226
	v_add_f32_e32 v227, 1.0, v227
	v_add_f32_e32 v228, 1.0, v228
	v_add_f32_e32 v229, 1.0, v229
	v_add_f32_e32 v230, 1.0, v230
	v_rcp_f32_e64 v224, -v224
	v_rcp_f32_e64 v225, -v225
	v_rcp_f32_e64 v226, -v226
	v_rcp_f32_e64 v227, -v227
	v_rcp_f32_e64 v228, -v228
	v_rcp_f32_e64 v229, -v229
	v_rcp_f32_e64 v230, -v230
	v_mul_f32_e32 v169, v249, v224
	v_mul_f32_e32 v170, v250, v225
	v_mul_f32_e32 v171, v251, v226
	v_mul_f32_e32 v232, v253, v227
	v_mul_f32_e32 v220, v254, v228
	v_mul_f32_e32 v166, v255, v229
	v_mul_f32_e32 v164, v219, v230
	v_add_f32_e32 v224, v169, v169
	v_add_f32_e32 v225, v170, v170
	v_add_f32_e32 v226, v171, v171
	v_add_f32_e32 v227, v232, v232
	v_add_f32_e32 v228, v220, v220
	v_add_f32_e32 v229, v166, v166
	v_add_f32_e32 v230, v164, v164
	v_fmamk_f32 v215, v224, 0x3c088889, v212
	v_fmamk_f32 v216, v225, 0x3c088889, v212
	v_fmamk_f32 v217, v226, 0x3c088889, v212
	v_fmamk_f32 v221, v227, 0x3c088889, v212
	v_fmamk_f32 v222, v228, 0x3c088889, v212
	v_fmamk_f32 v223, v229, 0x3c088889, v212
	v_fmamk_f32 v165, v230, 0x3c088889, v212
	v_fmaak_f32 v215, v224, v215, 0x3e2aaaab
	v_fmaak_f32 v216, v225, v216, 0x3e2aaaab
	v_fmaak_f32 v217, v226, v217, 0x3e2aaaab
	v_fmaak_f32 v221, v227, v221, 0x3e2aaaab
	v_fmaak_f32 v222, v228, v222, 0x3e2aaaab
	v_fmaak_f32 v223, v229, v223, 0x3e2aaaab
	v_fmaak_f32 v165, v230, v165, 0x3e2aaaab
	v_fma_f32 v215, v224, v215, 0.5
	v_fma_f32 v216, v225, v216, 0.5
	v_fma_f32 v217, v226, v217, 0.5
	v_fma_f32 v221, v227, v221, 0.5
	v_fma_f32 v222, v228, v222, 0.5
	v_fma_f32 v223, v229, v223, 0.5
	v_fma_f32 v165, v230, v165, 0.5
	v_fma_f32 v215, v224, v215, 1.0
	v_fma_f32 v216, v225, v216, 1.0
	v_fma_f32 v217, v226, v217, 1.0
	v_fma_f32 v221, v227, v221, 1.0
	v_fma_f32 v222, v228, v222, 1.0
	v_fma_f32 v223, v229, v223, 1.0
	v_fma_f32 v165, v230, v165, 1.0
	v_mul_f32_e64 v215, v215, -v224
	v_mul_f32_e64 v216, v216, -v225
	v_mul_f32_e64 v217, v217, -v226
	v_mul_f32_e64 v221, v221, -v227
	v_mul_f32_e64 v222, v222, -v228
	v_mul_f32_e64 v223, v223, -v229
	v_mul_f32_e64 v165, v165, -v230
	v_min3_f32 v231, v224, v225, v226
	v_min3_f32 v231, v231, v227, v228
	v_min3_f32 v231, v231, v229, v230
	v_cmp_gt_f32_e32 vcc, s72, v231
	s_cbranch_vccnz .Lp3_rare_0
; __device__ __forceinline__ float fsigmoid(float x) { return __builtin_amdgcn_rcpf(1.0f + __builtin_amdgcn_exp2f(-x * LOG2E)); }
; __device__ __forceinline__ void unpack8(u32x4 w, f32x4& a, f32x4& b) { a = (f32x4){bf_lo(w.x), bf_hi(w.x), bf_lo(w.y), bf_hi(w.y)}; b = (f32x4){bf_lo(w.z), bf_hi(w.z), bf_lo(w.w), bf_hi(w.w)}; }
; #define ST16(BASE, OFF, VAL) __builtin_amdgcn_raw_buffer_store_b128((VAL), __builtin_amdgcn_make_buffer_rsrc((void*)(BASE), (short)0, 0x7ffffff0, 0x00020000), (int)((unsigned)(OFF) * (unsigned)sizeof(*(BASE))), 0, ST_AUX)
; __device__ __forceinline__ unsigned pack_h2(float lo, float hi) { const __half2 h = __floats2half2_rn(lo, hi); return *(const unsigned*)&h; }
;     __device__ __forceinline__ void operator()(const Acc& acc, const Unit& u, int wr, int wc, int fr, int fq) const {
;     ...
;             for (int m = 0; m < 4; ++m) { const unsigned row = rowt + ai * 128 + m * 16;
;                 f32x4 x0, x1; unpack8(xw[ai * 4 + m], x0, x1);
;                 u32x4 o0, o1;
; #pragma unroll
;                 for (int h = 0; h < 2; ++h) { const f32x4 ar = acc[ai][0][m][h] + cbr[h], aiq = acc[ai][1][m][h] + cbi[h], sp = csp[h], xx = h ? x1 : x0; u32x4 o;
; #pragma unroll
;                     for (int e = 0; e < 4; ++e) { const float rr = fsigmoid(ar[e]), ii = fsigmoid(aiq[e]); const float la = -rr * sp[e], y = 2.0f * la;
;                         float m2 = -y * (1.0f + y * (0.5f + y * (0.16666667f + y * (0.041666668f + y * 0.0083333338f))));
;                         if (__builtin_expect(__any(y < -0.25f), 0)) m2 = (y < -0.25f) ? 1.0f - __builtin_amdgcn_exp2f(y * LOG2E) : m2;
;                         const float uu = ii * xx[e] * __builtin_amdgcn_sqrtf(m2); o[e] = pack_h2(la * LOG2E, uu); }
;                     if (h) o1 = o; else o0 = o; }
;                 ST16(dst, (row * 512 + ch), o0); ST16(dst, (row * 512 + ch + 4), o1); }
.Lp3_ret_0:
.LBB0_552:
	s_waitcnt vmcnt(0)
	v_add_f32_e32 v160, v160, v56
	v_mul_f32_e32 v160, 0xbfb8aa3b, v160
	v_exp_f32_e32 v160, v160
	v_add_f32_e32 v161, v161, v57
	v_mul_f32_e32 v161, 0xbfb8aa3b, v161
	v_exp_f32_e32 v161, v161
	v_add_f32_e32 v160, 1.0, v160
	v_rcp_f32_e32 v160, v160
	v_add_f32_e32 v162, v162, v58
	v_mul_f32_e32 v162, 0xbfb8aa3b, v162
	v_add_f32_e32 v161, 1.0, v161
	v_exp_f32_e32 v162, v162
	v_lshlrev_b32_e32 v167, 16, v182
	v_rcp_f32_e32 v161, v161
	v_mul_f32_e32 v160, v160, v167
	v_and_b32_e32 v167, 0xffff0000, v182
	v_sqrt_f32_e32 v182, v222
	v_add_f32_e32 v156, v156, v64
	v_add_f32_e32 v162, 1.0, v162
	v_mul_f32_e32 v156, 0xbfb8aa3b, v156
	v_mul_f32_e32 v161, v161, v167
	v_rcp_f32_e32 v162, v162
	v_exp_f32_e32 v156, v156
	v_mul_f32_e32 v161, v161, v182
	v_sqrt_f32_e32 v182, v223
	v_add_f32_e32 v157, v157, v65
	v_mul_f32_e32 v167, 0x3fb8aa3b, v220
	v_mul_f32_e32 v157, 0xbfb8aa3b, v157
	v_cvt_pk_f16_f32 v161, v167, v161
	v_lshlrev_b32_e32 v167, 16, v183
	v_exp_f32_e32 v157, v157
	v_mul_f32_e32 v162, v162, v167
	v_add_f32_e32 v156, 1.0, v156
	v_mul_f32_e32 v162, v162, v182
	v_mul_f32_e32 v166, 0x3fb8aa3b, v166
	v_rcp_f32_e32 v156, v156
	v_cvt_pk_f16_f32 v162, v166, v162
	v_sqrt_f32_e32 v166, v192
	v_add_f32_e32 v157, 1.0, v157
	v_add_f32_e32 v158, v158, v66
	v_lshlrev_b32_e32 v167, 16, v180
	v_rcp_f32_e32 v157, v157
	v_mul_f32_e32 v158, 0xbfb8aa3b, v158
	v_mul_f32_e32 v156, v156, v167
	v_exp_f32_e32 v158, v158
	v_mul_f32_e32 v156, v156, v166
	v_mul_f32_e32 v166, 0x3fb8aa3b, v168
	v_cvt_pk_f16_f32 v156, v166, v156
	v_and_b32_e32 v166, 0xffff0000, v180
	v_add_f32_e32 v159, v159, v67
	v_mul_f32_e32 v157, v157, v166
	v_sqrt_f32_e32 v166, v215
	v_mul_f32_e32 v159, 0xbfb8aa3b, v159
	v_add_f32_e32 v158, 1.0, v158
	v_exp_f32_e32 v159, v159
	v_add_f32_e32 v163, v163, v59
	v_rcp_f32_e32 v158, v158
	v_mul_f32_e32 v163, 0xbfb8aa3b, v163
	v_sqrt_f32_e32 v167, v216
	v_exp_f32_e32 v163, v163
	v_mul_f32_e32 v157, v157, v166
	v_mul_f32_e32 v166, 0x3fb8aa3b, v169
	v_cvt_pk_f16_f32 v157, v166, v157
	v_lshlrev_b32_e32 v166, 16, v181
	v_add_f32_e32 v159, 1.0, v159
	v_mul_f32_e32 v158, v158, v166
	v_rcp_f32_e32 v159, v159
	v_mul_f32_e32 v158, v158, v167
	v_sqrt_f32_e32 v167, v217
	v_add_f32_e32 v148, v148, v240
	v_add_f32_e32 v163, 1.0, v163
	v_mul_f32_e32 v166, 0x3fb8aa3b, v170
	v_mul_f32_e32 v148, 0xbfb8aa3b, v148
	v_rcp_f32_e32 v163, v163
	v_cvt_pk_f16_f32 v158, v166, v158
	v_and_b32_e32 v166, 0xffff0000, v181
	v_exp_f32_e32 v148, v148
	v_mul_f32_e32 v159, v159, v166
	v_sqrt_f32_e32 v165, v165
	v_mul_f32_e32 v159, v159, v167
	v_mul_f32_e32 v166, 0x3fb8aa3b, v171
	v_cvt_pk_f16_f32 v159, v166, v159
	v_and_b32_e32 v166, 0xffff0000, v183
	v_sqrt_f32_e32 v221, v221
	v_mul_f32_e32 v163, v163, v166
	v_add_f32_e32 v148, 1.0, v148
	s_lshl_b32 s4, s5, 27
	v_mul_f32_e32 v163, v163, v165
	v_rcp_f32_e64 v165, -v148
	s_add_u32 s4, s20, s4
	v_mul_f32_e32 v164, 0x3fb8aa3b, v164
	s_addc_u32 s5, s21, 0
	v_cvt_pk_f16_f32 v163, v164, v163
	v_lshlrev_b32_e32 v164, 2, v214
	v_mul_f32_e32 v232, 0x3fb8aa3b, v232
	v_mul_f32_e32 v160, v160, v221
	s_and_b32 s5, s5, 0xffff
	v_lshl_add_u32 v148, v213, 11, v164
	v_cvt_pk_f16_f32 v160, v232, v160
	buffer_store_dwordx4 v[156:159], v148, s[4:7], 0 offen nt
	buffer_store_dwordx4 v[160:163], v148, s[4:7], 0 offen offset:16 nt
	s_nop 0
	v_mul_f32_e32 v156, v248, v165
	v_add_f32_e32 v158, v156, v156
	v_fmamk_f32 v157, v158, 0x3c088889, v212
	v_fmaak_f32 v157, v158, v157, 0x3e2aaaab
	v_fma_f32 v157, v158, v157, 0.5
	v_fma_f32 v157, v158, v157, 1.0
	v_mul_f32_e64 v157, v157, -v158
	v_cmp_gt_f32_e32 vcc, s72, v158
	s_cbranch_vccnz .LBB0_619
.LBB0_553:
	v_add_f32_e32 v224, v149, v241
	v_add_f32_e32 v225, v150, v242
	v_add_f32_e32 v226, v151, v243
	v_add_f32_e32 v227, v144, v244
	v_add_f32_e32 v228, v145, v245
	v_add_f32_e32 v229, v146, v246
	v_add_f32_e32 v230, v147, v247
	v_mul_f32_e32 v224, 0xbfb8aa3b, v224
	v_mul_f32_e32 v225, 0xbfb8aa3b, v225
	v_mul_f32_e32 v226, 0xbfb8aa3b, v226
	v_mul_f32_e32 v227, 0xbfb8aa3b, v227
	v_mul_f32_e32 v228, 0xbfb8aa3b, v228
	v_mul_f32_e32 v229, 0xbfb8aa3b, v229
	v_mul_f32_e32 v230, 0xbfb8aa3b, v230
	v_exp_f32_e32 v224, v224
	v_exp_f32_e32 v225, v225
	v_exp_f32_e32 v226, v226
	v_exp_f32_e32 v227, v227
	v_exp_f32_e32 v228, v228
	v_exp_f32_e32 v229, v229
	v_exp_f32_e32 v230, v230
	v_add_f32_e32 v224, 1.0, v224
	v_add_f32_e32 v225, 1.0, v225
	v_add_f32_e32 v226, 1.0, v226
	v_add_f32_e32 v227, 1.0, v227
	v_add_f32_e32 v228, 1.0, v228
	v_add_f32_e32 v229, 1.0, v229
	v_add_f32_e32 v230, 1.0, v230
	v_rcp_f32_e64 v224, -v224
	v_rcp_f32_e64 v225, -v225
	v_rcp_f32_e64 v226, -v226
	v_rcp_f32_e64 v227, -v227
	v_rcp_f32_e64 v228, -v228
	v_rcp_f32_e64 v229, -v229
	v_rcp_f32_e64 v230, -v230
	v_mul_f32_e32 v149, v249, v224
	v_mul_f32_e32 v150, v250, v225
	v_mul_f32_e32 v151, v251, v226
	v_mul_f32_e32 v161, v253, v227
	v_mul_f32_e32 v162, v254, v228
	v_mul_f32_e32 v146, v255, v229
	v_mul_f32_e32 v144, v219, v230
	v_add_f32_e32 v224, v149, v149
	v_add_f32_e32 v225, v150, v150
	v_add_f32_e32 v226, v151, v151
	v_add_f32_e32 v227, v161, v161
	v_add_f32_e32 v228, v162, v162
	v_add_f32_e32 v229, v146, v146
	v_add_f32_e32 v230, v144, v144
	v_fmamk_f32 v158, v224, 0x3c088889, v212
	v_fmamk_f32 v159, v225, 0x3c088889, v212
	v_fmamk_f32 v160, v226, 0x3c088889, v212
	v_fmamk_f32 v163, v227, 0x3c088889, v212
	v_fmamk_f32 v164, v228, 0x3c088889, v212
	v_fmamk_f32 v165, v229, 0x3c088889, v212
	v_fmamk_f32 v145, v230, 0x3c088889, v212
	v_fmaak_f32 v158, v224, v158, 0x3e2aaaab
	v_fmaak_f32 v159, v225, v159, 0x3e2aaaab
	v_fmaak_f32 v160, v226, v160, 0x3e2aaaab
	v_fmaak_f32 v163, v227, v163, 0x3e2aaaab
	v_fmaak_f32 v164, v228, v164, 0x3e2aaaab
	v_fmaak_f32 v165, v229, v165, 0x3e2aaaab
	v_fmaak_f32 v145, v230, v145, 0x3e2aaaab
	v_fma_f32 v158, v224, v158, 0.5
	v_fma_f32 v159, v225, v159, 0.5
	v_fma_f32 v160, v226, v160, 0.5
	v_fma_f32 v163, v227, v163, 0.5
	v_fma_f32 v164, v228, v164, 0.5
	v_fma_f32 v165, v229, v165, 0.5
	v_fma_f32 v145, v230, v145, 0.5
	v_fma_f32 v158, v224, v158, 1.0
	v_fma_f32 v159, v225, v159, 1.0
	v_fma_f32 v160, v226, v160, 1.0
	v_fma_f32 v163, v227, v163, 1.0
	v_fma_f32 v164, v228, v164, 1.0
	v_fma_f32 v165, v229, v165, 1.0
	v_fma_f32 v145, v230, v145, 1.0
	v_mul_f32_e64 v158, v158, -v224
	v_mul_f32_e64 v159, v159, -v225
	v_mul_f32_e64 v160, v160, -v226
	v_mul_f32_e64 v163, v163, -v227
	v_mul_f32_e64 v164, v164, -v228
	v_mul_f32_e64 v165, v165, -v229
	v_mul_f32_e64 v145, v145, -v230
	v_min3_f32 v231, v224, v225, v226
	v_min3_f32 v231, v231, v227, v228
	v_min3_f32 v231, v231, v229, v230
	v_cmp_gt_f32_e32 vcc, s72, v231
	s_cbranch_vccnz .Lp3_rare_1
; __device__ __forceinline__ float fsigmoid(float x) { return __builtin_amdgcn_rcpf(1.0f + __builtin_amdgcn_exp2f(-x * LOG2E)); }
; __device__ __forceinline__ void unpack8(u32x4 w, f32x4& a, f32x4& b) { a = (f32x4){bf_lo(w.x), bf_hi(w.x), bf_lo(w.y), bf_hi(w.y)}; b = (f32x4){bf_lo(w.z), bf_hi(w.z), bf_lo(w.w), bf_hi(w.w)}; }
; #define ST16(BASE, OFF, VAL) __builtin_amdgcn_raw_buffer_store_b128((VAL), __builtin_amdgcn_make_buffer_rsrc((void*)(BASE), (short)0, 0x7ffffff0, 0x00020000), (int)((unsigned)(OFF) * (unsigned)sizeof(*(BASE))), 0, ST_AUX)
; __device__ __forceinline__ unsigned pack_h2(float lo, float hi) { const __half2 h = __floats2half2_rn(lo, hi); return *(const unsigned*)&h; }
;     __device__ __forceinline__ void operator()(const Acc& acc, const Unit& u, int wr, int wc, int fr, int fq) const {
;     ...
;             for (int m = 0; m < 4; ++m) { const unsigned row = rowt + ai * 128 + m * 16;
;                 f32x4 x0, x1; unpack8(xw[ai * 4 + m], x0, x1);
;                 u32x4 o0, o1;
; #pragma unroll
;                 for (int h = 0; h < 2; ++h) { const f32x4 ar = acc[ai][0][m][h] + cbr[h], aiq = acc[ai][1][m][h] + cbi[h], sp = csp[h], xx = h ? x1 : x0; u32x4 o;
; #pragma unroll
;                     for (int e = 0; e < 4; ++e) { const float rr = fsigmoid(ar[e]), ii = fsigmoid(aiq[e]); const float la = -rr * sp[e], y = 2.0f * la;
;                         float m2 = -y * (1.0f + y * (0.5f + y * (0.16666667f + y * (0.041666668f + y * 0.0083333338f))));
;                         if (__builtin_expect(__any(y < -0.25f), 0)) m2 = (y < -0.25f) ? 1.0f - __builtin_amdgcn_exp2f(y * LOG2E) : m2;
;                         const float uu = ii * xx[e] * __builtin_amdgcn_sqrtf(m2); o[e] = pack_h2(la * LOG2E, uu); }
;                     if (h) o1 = o; else o0 = o; }
;                 ST16(dst, (row * 512 + ch), o0); ST16(dst, (row * 512 + ch + 4), o1); }
.Lp3_ret_1:
.LBB0_560:
	v_add_f32_e32 v140, v140, v56
	v_mul_f32_e32 v140, 0xbfb8aa3b, v140
	v_exp_f32_e32 v140, v140
	v_add_f32_e32 v141, v141, v57
	v_mul_f32_e32 v141, 0xbfb8aa3b, v141
	v_exp_f32_e32 v141, v141
	v_add_f32_e32 v140, 1.0, v140
	v_rcp_f32_e32 v140, v140
	v_sqrt_f32_e32 v163, v163
	v_add_f32_e32 v142, v142, v58
	v_lshlrev_b32_e32 v147, 16, v178
	v_mul_f32_e32 v142, 0xbfb8aa3b, v142
	v_mul_f32_e32 v140, v140, v147
	v_add_f32_e32 v141, 1.0, v141
	v_exp_f32_e32 v142, v142
	v_mul_f32_e32 v161, 0x3fb8aa3b, v161
	v_mul_f32_e32 v140, v140, v163
	v_rcp_f32_e32 v141, v141
	v_cvt_pk_f16_f32 v140, v161, v140
	v_sqrt_f32_e32 v161, v164
	v_add_f32_e32 v132, v132, v64
	v_and_b32_e32 v147, 0xffff0000, v178
	v_add_f32_e32 v142, 1.0, v142
	v_mul_f32_e32 v132, 0xbfb8aa3b, v132
	v_mul_f32_e32 v141, v141, v147
	v_rcp_f32_e32 v142, v142
	v_exp_f32_e32 v132, v132
	v_mul_f32_e32 v141, v141, v161
	v_sqrt_f32_e32 v161, v165
	v_add_f32_e32 v133, v133, v65
	v_mul_f32_e32 v147, 0x3fb8aa3b, v162
	v_mul_f32_e32 v133, 0xbfb8aa3b, v133
	v_cvt_pk_f16_f32 v141, v147, v141
	v_lshlrev_b32_e32 v147, 16, v179
	v_exp_f32_e32 v133, v133
	v_mul_f32_e32 v142, v142, v147
	v_add_f32_e32 v132, 1.0, v132
	v_mul_f32_e32 v142, v142, v161
	v_mul_f32_e32 v146, 0x3fb8aa3b, v146
	v_rcp_f32_e32 v132, v132
	v_cvt_pk_f16_f32 v142, v146, v142
	v_sqrt_f32_e32 v146, v157
	v_add_f32_e32 v133, 1.0, v133
	v_add_f32_e32 v134, v134, v66
	v_lshlrev_b32_e32 v147, 16, v176
	v_rcp_f32_e32 v133, v133
	v_mul_f32_e32 v134, 0xbfb8aa3b, v134
	v_mul_f32_e32 v132, v132, v147
	v_exp_f32_e32 v134, v134
	v_mul_f32_e32 v132, v132, v146
	v_mul_f32_e32 v146, 0x3fb8aa3b, v156
	v_cvt_pk_f16_f32 v132, v146, v132
	v_and_b32_e32 v146, 0xffff0000, v176
	v_add_f32_e32 v135, v135, v67
	v_mul_f32_e32 v133, v133, v146
	v_sqrt_f32_e32 v146, v158
	v_mul_f32_e32 v135, 0xbfb8aa3b, v135
	v_add_f32_e32 v134, 1.0, v134
	v_exp_f32_e32 v135, v135
	v_add_f32_e32 v143, v143, v59
	v_rcp_f32_e32 v134, v134
	v_mul_f32_e32 v143, 0xbfb8aa3b, v143
	v_sqrt_f32_e32 v147, v159
	v_exp_f32_e32 v143, v143
	v_mul_f32_e32 v133, v133, v146
	v_mul_f32_e32 v146, 0x3fb8aa3b, v149
	v_add_f32_e32 v128, v128, v240
	v_cvt_pk_f16_f32 v133, v146, v133
	v_lshlrev_b32_e32 v146, 16, v177
	v_add_f32_e32 v135, 1.0, v135
	v_mul_f32_e32 v128, 0xbfb8aa3b, v128
	v_mul_f32_e32 v134, v134, v146
	v_rcp_f32_e32 v135, v135
	v_exp_f32_e32 v128, v128
	v_mul_f32_e32 v134, v134, v147
	v_sqrt_f32_e32 v147, v160
	v_add_f32_e32 v143, 1.0, v143
	v_mul_f32_e32 v146, 0x3fb8aa3b, v150
	v_rcp_f32_e32 v143, v143
	v_cvt_pk_f16_f32 v134, v146, v134
	v_and_b32_e32 v146, 0xffff0000, v177
	v_mul_f32_e32 v135, v135, v146
	v_sqrt_f32_e32 v145, v145
	v_add_f32_e32 v128, 1.0, v128
	v_mul_f32_e32 v135, v135, v147
	v_mul_f32_e32 v146, 0x3fb8aa3b, v151
	v_rcp_f32_e64 v128, -v128
	v_cvt_pk_f16_f32 v135, v146, v135
	v_and_b32_e32 v146, 0xffff0000, v179
	v_mul_f32_e32 v143, v143, v146
	v_mul_f32_e32 v143, v143, v145
	v_mul_f32_e32 v144, 0x3fb8aa3b, v144
	v_cvt_pk_f16_f32 v143, v144, v143
	v_add_u32_e32 v144, 0x8000, v148
	v_mul_f32_e32 v128, v248, v128
	buffer_store_dwordx4 v[132:135], v144, s[4:7], 0 offen nt
	buffer_store_dwordx4 v[140:143], v144, s[4:7], 0 offen offset:16 nt
	s_nop 0
	v_add_f32_e32 v133, v128, v128
	v_fmamk_f32 v132, v133, 0x3c088889, v212
	v_fmaak_f32 v132, v133, v132, 0x3e2aaaab
	v_fma_f32 v132, v133, v132, 0.5
	v_fma_f32 v132, v133, v132, 1.0
	v_mul_f32_e64 v132, v132, -v133
	v_cmp_gt_f32_e32 vcc, s72, v133
	s_cbranch_vccnz .LBB0_627
.LBB0_561:
	v_add_f32_e32 v224, v129, v241
	v_add_f32_e32 v225, v130, v242
	v_add_f32_e32 v226, v131, v243
	v_add_f32_e32 v227, v124, v244
	v_add_f32_e32 v228, v125, v245
	v_add_f32_e32 v229, v126, v246
	v_add_f32_e32 v230, v127, v247
	v_mul_f32_e32 v224, 0xbfb8aa3b, v224
	v_mul_f32_e32 v225, 0xbfb8aa3b, v225
	v_mul_f32_e32 v226, 0xbfb8aa3b, v226
	v_mul_f32_e32 v227, 0xbfb8aa3b, v227
	v_mul_f32_e32 v228, 0xbfb8aa3b, v228
	v_mul_f32_e32 v229, 0xbfb8aa3b, v229
	v_mul_f32_e32 v230, 0xbfb8aa3b, v230
	v_exp_f32_e32 v224, v224
	v_exp_f32_e32 v225, v225
	v_exp_f32_e32 v226, v226
	v_exp_f32_e32 v227, v227
	v_exp_f32_e32 v228, v228
	v_exp_f32_e32 v229, v229
	v_exp_f32_e32 v230, v230
	v_add_f32_e32 v224, 1.0, v224
	v_add_f32_e32 v225, 1.0, v225
	v_add_f32_e32 v226, 1.0, v226
	v_add_f32_e32 v227, 1.0, v227
	v_add_f32_e32 v228, 1.0, v228
	v_add_f32_e32 v229, 1.0, v229
	v_add_f32_e32 v230, 1.0, v230
	v_rcp_f32_e64 v224, -v224
	v_rcp_f32_e64 v225, -v225
	v_rcp_f32_e64 v226, -v226
	v_rcp_f32_e64 v227, -v227
	v_rcp_f32_e64 v228, -v228
	v_rcp_f32_e64 v229, -v229
	v_rcp_f32_e64 v230, -v230
	v_mul_f32_e32 v129, v249, v224
	v_mul_f32_e32 v130, v250, v225
	v_mul_f32_e32 v131, v251, v226
	v_mul_f32_e32 v140, v253, v227
	v_mul_f32_e32 v141, v254, v228
	v_mul_f32_e32 v126, v255, v229
	v_mul_f32_e32 v124, v219, v230
	v_add_f32_e32 v224, v129, v129
	v_add_f32_e32 v225, v130, v130
	v_add_f32_e32 v226, v131, v131
	v_add_f32_e32 v227, v140, v140
	v_add_f32_e32 v228, v141, v141
	v_add_f32_e32 v229, v126, v126
	v_add_f32_e32 v230, v124, v124
	v_fmamk_f32 v133, v224, 0x3c088889, v212
	v_fmamk_f32 v134, v225, 0x3c088889, v212
	v_fmamk_f32 v135, v226, 0x3c088889, v212
	v_fmamk_f32 v142, v227, 0x3c088889, v212
	v_fmamk_f32 v143, v228, 0x3c088889, v212
	v_fmamk_f32 v144, v229, 0x3c088889, v212
	v_fmamk_f32 v125, v230, 0x3c088889, v212
	v_fmaak_f32 v133, v224, v133, 0x3e2aaaab
	v_fmaak_f32 v134, v225, v134, 0x3e2aaaab
	v_fmaak_f32 v135, v226, v135, 0x3e2aaaab
	v_fmaak_f32 v142, v227, v142, 0x3e2aaaab
	v_fmaak_f32 v143, v228, v143, 0x3e2aaaab
	v_fmaak_f32 v144, v229, v144, 0x3e2aaaab
	v_fmaak_f32 v125, v230, v125, 0x3e2aaaab
	v_fma_f32 v133, v224, v133, 0.5
	v_fma_f32 v134, v225, v134, 0.5
	v_fma_f32 v135, v226, v135, 0.5
	v_fma_f32 v142, v227, v142, 0.5
	v_fma_f32 v143, v228, v143, 0.5
	v_fma_f32 v144, v229, v144, 0.5
	v_fma_f32 v125, v230, v125, 0.5
	v_fma_f32 v133, v224, v133, 1.0
	v_fma_f32 v134, v225, v134, 1.0
	v_fma_f32 v135, v226, v135, 1.0
	v_fma_f32 v142, v227, v142, 1.0
	v_fma_f32 v143, v228, v143, 1.0
	v_fma_f32 v144, v229, v144, 1.0
	v_fma_f32 v125, v230, v125, 1.0
	v_mul_f32_e64 v133, v133, -v224
	v_mul_f32_e64 v134, v134, -v225
	v_mul_f32_e64 v135, v135, -v226
	v_mul_f32_e64 v142, v142, -v227
	v_mul_f32_e64 v143, v143, -v228
	v_mul_f32_e64 v144, v144, -v229
	v_mul_f32_e64 v125, v125, -v230
	v_min3_f32 v231, v224, v225, v226
	v_min3_f32 v231, v231, v227, v228
	v_min3_f32 v231, v231, v229, v230
	v_cmp_gt_f32_e32 vcc, s72, v231
	s_cbranch_vccnz .Lp3_rare_2
; __device__ __forceinline__ float fsigmoid(float x) { return __builtin_amdgcn_rcpf(1.0f + __builtin_amdgcn_exp2f(-x * LOG2E)); }
; __device__ __forceinline__ void unpack8(u32x4 w, f32x4& a, f32x4& b) { a = (f32x4){bf_lo(w.x), bf_hi(w.x), bf_lo(w.y), bf_hi(w.y)}; b = (f32x4){bf_lo(w.z), bf_hi(w.z), bf_lo(w.w), bf_hi(w.w)}; }
; #define ST16(BASE, OFF, VAL) __builtin_amdgcn_raw_buffer_store_b128((VAL), __builtin_amdgcn_make_buffer_rsrc((void*)(BASE), (short)0, 0x7ffffff0, 0x00020000), (int)((unsigned)(OFF) * (unsigned)sizeof(*(BASE))), 0, ST_AUX)
; __device__ __forceinline__ unsigned pack_h2(float lo, float hi) { const __half2 h = __floats2half2_rn(lo, hi); return *(const unsigned*)&h; }
;     __device__ __forceinline__ void operator()(const Acc& acc, const Unit& u, int wr, int wc, int fr, int fq) const {
;     ...
;             for (int m = 0; m < 4; ++m) { const unsigned row = rowt + ai * 128 + m * 16;
;                 f32x4 x0, x1; unpack8(xw[ai * 4 + m], x0, x1);
;                 u32x4 o0, o1;
; #pragma unroll
;                 for (int h = 0; h < 2; ++h) { const f32x4 ar = acc[ai][0][m][h] + cbr[h], aiq = acc[ai][1][m][h] + cbi[h], sp = csp[h], xx = h ? x1 : x0; u32x4 o;
; #pragma unroll
;                     for (int e = 0; e < 4; ++e) { const float rr = fsigmoid(ar[e]), ii = fsigmoid(aiq[e]); const float la = -rr * sp[e], y = 2.0f * la;
;                         float m2 = -y * (1.0f + y * (0.5f + y * (0.16666667f + y * (0.041666668f + y * 0.0083333338f))));
;                         if (__builtin_expect(__any(y < -0.25f), 0)) m2 = (y < -0.25f) ? 1.0f - __builtin_amdgcn_exp2f(y * LOG2E) : m2;
;                         const float uu = ii * xx[e] * __builtin_amdgcn_sqrtf(m2); o[e] = pack_h2(la * LOG2E, uu); }
;                     if (h) o1 = o; else o0 = o; }
;                 ST16(dst, (row * 512 + ch), o0); ST16(dst, (row * 512 + ch + 4), o1); }
.Lp3_ret_2:
.LBB0_568:
	v_add_f32_e32 v120, v120, v56
	v_mul_f32_e32 v120, 0xbfb8aa3b, v120
	v_exp_f32_e32 v120, v120
	v_add_f32_e32 v121, v121, v57
	v_mul_f32_e32 v121, 0xbfb8aa3b, v121
	v_exp_f32_e32 v121, v121
	v_add_f32_e32 v120, 1.0, v120
	v_rcp_f32_e32 v120, v120
	v_sqrt_f32_e32 v142, v142
	v_add_f32_e32 v122, v122, v58
	v_lshlrev_b32_e32 v127, 16, v174
	v_mul_f32_e32 v122, 0xbfb8aa3b, v122
	v_mul_f32_e32 v120, v120, v127
	v_add_f32_e32 v121, 1.0, v121
	v_exp_f32_e32 v122, v122
	v_mul_f32_e32 v140, 0x3fb8aa3b, v140
	v_mul_f32_e32 v120, v120, v142
	v_rcp_f32_e32 v121, v121
	v_cvt_pk_f16_f32 v120, v140, v120
	v_sqrt_f32_e32 v140, v143
	v_add_f32_e32 v112, v112, v64
	v_and_b32_e32 v127, 0xffff0000, v174
	v_add_f32_e32 v122, 1.0, v122
	v_mul_f32_e32 v112, 0xbfb8aa3b, v112
	v_mul_f32_e32 v121, v121, v127
	v_rcp_f32_e32 v122, v122
	v_exp_f32_e32 v112, v112
	v_mul_f32_e32 v121, v121, v140
	v_sqrt_f32_e32 v140, v144
	v_add_f32_e32 v113, v113, v65
	v_mul_f32_e32 v127, 0x3fb8aa3b, v141
	v_mul_f32_e32 v113, 0xbfb8aa3b, v113
	v_cvt_pk_f16_f32 v121, v127, v121
	v_lshlrev_b32_e32 v127, 16, v175
	v_exp_f32_e32 v113, v113
	v_mul_f32_e32 v122, v122, v127
	v_add_f32_e32 v112, 1.0, v112
	v_mul_f32_e32 v122, v122, v140
	v_mul_f32_e32 v126, 0x3fb8aa3b, v126
	v_rcp_f32_e32 v112, v112
	v_cvt_pk_f16_f32 v122, v126, v122
	v_sqrt_f32_e32 v126, v132
	v_add_f32_e32 v113, 1.0, v113
	v_add_f32_e32 v114, v114, v66
	v_lshlrev_b32_e32 v127, 16, v172
	v_rcp_f32_e32 v113, v113
	v_mul_f32_e32 v114, 0xbfb8aa3b, v114
	v_mul_f32_e32 v112, v112, v127
	v_exp_f32_e32 v114, v114
	v_mul_f32_e32 v112, v112, v126
	v_mul_f32_e32 v126, 0x3fb8aa3b, v128
	v_cvt_pk_f16_f32 v112, v126, v112
	v_and_b32_e32 v126, 0xffff0000, v172
	v_add_f32_e32 v115, v115, v67
	v_mul_f32_e32 v113, v113, v126
	v_sqrt_f32_e32 v126, v133
	v_mul_f32_e32 v115, 0xbfb8aa3b, v115
	v_add_f32_e32 v114, 1.0, v114
	v_exp_f32_e32 v115, v115
	v_add_f32_e32 v123, v123, v59
	v_rcp_f32_e32 v114, v114
	v_mul_f32_e32 v123, 0xbfb8aa3b, v123
	v_sqrt_f32_e32 v127, v134
	v_exp_f32_e32 v123, v123
	v_mul_f32_e32 v113, v113, v126
	v_mul_f32_e32 v126, 0x3fb8aa3b, v129
	v_add_f32_e32 v108, v108, v240
	v_cvt_pk_f16_f32 v113, v126, v113
	v_lshlrev_b32_e32 v126, 16, v173
	v_add_f32_e32 v115, 1.0, v115
	v_mul_f32_e32 v108, 0xbfb8aa3b, v108
	v_mul_f32_e32 v114, v114, v126
	v_rcp_f32_e32 v115, v115
	v_exp_f32_e32 v108, v108
	v_mul_f32_e32 v114, v114, v127
	v_sqrt_f32_e32 v127, v135
	v_add_f32_e32 v123, 1.0, v123
	v_mul_f32_e32 v126, 0x3fb8aa3b, v130
	v_rcp_f32_e32 v123, v123
	v_cvt_pk_f16_f32 v114, v126, v114
	v_and_b32_e32 v126, 0xffff0000, v173
	v_mul_f32_e32 v115, v115, v126
	v_sqrt_f32_e32 v125, v125
	v_add_f32_e32 v108, 1.0, v108
	v_mul_f32_e32 v115, v115, v127
	v_mul_f32_e32 v126, 0x3fb8aa3b, v131
	v_rcp_f32_e64 v108, -v108
	v_cvt_pk_f16_f32 v115, v126, v115
	v_and_b32_e32 v126, 0xffff0000, v175
	v_mul_f32_e32 v123, v123, v126
	v_mul_f32_e32 v123, v123, v125
	v_mul_f32_e32 v124, 0x3fb8aa3b, v124
	v_cvt_pk_f16_f32 v123, v124, v123
	v_add_u32_e32 v124, 0x10000, v148
	v_mul_f32_e32 v108, v248, v108
	buffer_store_dwordx4 v[112:115], v124, s[4:7], 0 offen nt
	buffer_store_dwordx4 v[120:123], v124, s[4:7], 0 offen offset:16 nt
	s_nop 0
	v_add_f32_e32 v113, v108, v108
	v_fmamk_f32 v112, v113, 0x3c088889, v212
	v_fmaak_f32 v112, v113, v112, 0x3e2aaaab
	v_fma_f32 v112, v113, v112, 0.5
	v_fma_f32 v112, v113, v112, 1.0
	v_mul_f32_e64 v112, v112, -v113
	v_cmp_gt_f32_e32 vcc, s72, v113
	s_cbranch_vccnz .LBB0_635
.LBB0_569:
	v_add_f32_e32 v224, v109, v241
	v_add_f32_e32 v225, v110, v242
	v_add_f32_e32 v226, v111, v243
	v_add_f32_e32 v227, v104, v244
	v_add_f32_e32 v228, v105, v245
	v_add_f32_e32 v229, v106, v246
	v_add_f32_e32 v230, v107, v247
	v_mul_f32_e32 v224, 0xbfb8aa3b, v224
	v_mul_f32_e32 v225, 0xbfb8aa3b, v225
	v_mul_f32_e32 v226, 0xbfb8aa3b, v226
	v_mul_f32_e32 v227, 0xbfb8aa3b, v227
	v_mul_f32_e32 v228, 0xbfb8aa3b, v228
	v_mul_f32_e32 v229, 0xbfb8aa3b, v229
	v_mul_f32_e32 v230, 0xbfb8aa3b, v230
	v_exp_f32_e32 v224, v224
	v_exp_f32_e32 v225, v225
	v_exp_f32_e32 v226, v226
	v_exp_f32_e32 v227, v227
	v_exp_f32_e32 v228, v228
	v_exp_f32_e32 v229, v229
	v_exp_f32_e32 v230, v230
	v_add_f32_e32 v224, 1.0, v224
	v_add_f32_e32 v225, 1.0, v225
	v_add_f32_e32 v226, 1.0, v226
	v_add_f32_e32 v227, 1.0, v227
	v_add_f32_e32 v228, 1.0, v228
	v_add_f32_e32 v229, 1.0, v229
	v_add_f32_e32 v230, 1.0, v230
	v_rcp_f32_e64 v224, -v224
	v_rcp_f32_e64 v225, -v225
	v_rcp_f32_e64 v226, -v226
	v_rcp_f32_e64 v227, -v227
	v_rcp_f32_e64 v228, -v228
	v_rcp_f32_e64 v229, -v229
	v_rcp_f32_e64 v230, -v230
	v_mul_f32_e32 v109, v249, v224
	v_mul_f32_e32 v110, v250, v225
	v_mul_f32_e32 v111, v251, v226
	v_mul_f32_e32 v120, v253, v227
	v_mul_f32_e32 v121, v254, v228
	v_mul_f32_e32 v106, v255, v229
	v_mul_f32_e32 v104, v219, v230
	v_add_f32_e32 v224, v109, v109
	v_add_f32_e32 v225, v110, v110
	v_add_f32_e32 v226, v111, v111
	v_add_f32_e32 v227, v120, v120
	v_add_f32_e32 v228, v121, v121
	v_add_f32_e32 v229, v106, v106
	v_add_f32_e32 v230, v104, v104
	v_fmamk_f32 v113, v224, 0x3c088889, v212
	v_fmamk_f32 v114, v225, 0x3c088889, v212
	v_fmamk_f32 v115, v226, 0x3c088889, v212
	v_fmamk_f32 v122, v227, 0x3c088889, v212
	v_fmamk_f32 v123, v228, 0x3c088889, v212
	v_fmamk_f32 v124, v229, 0x3c088889, v212
	v_fmamk_f32 v105, v230, 0x3c088889, v212
	v_fmaak_f32 v113, v224, v113, 0x3e2aaaab
	v_fmaak_f32 v114, v225, v114, 0x3e2aaaab
	v_fmaak_f32 v115, v226, v115, 0x3e2aaaab
	v_fmaak_f32 v122, v227, v122, 0x3e2aaaab
	v_fmaak_f32 v123, v228, v123, 0x3e2aaaab
	v_fmaak_f32 v124, v229, v124, 0x3e2aaaab
	v_fmaak_f32 v105, v230, v105, 0x3e2aaaab
	v_fma_f32 v113, v224, v113, 0.5
	v_fma_f32 v114, v225, v114, 0.5
	v_fma_f32 v115, v226, v115, 0.5
	v_fma_f32 v122, v227, v122, 0.5
	v_fma_f32 v123, v228, v123, 0.5
	v_fma_f32 v124, v229, v124, 0.5
	v_fma_f32 v105, v230, v105, 0.5
	v_fma_f32 v113, v224, v113, 1.0
	v_fma_f32 v114, v225, v114, 1.0
	v_fma_f32 v115, v226, v115, 1.0
	v_fma_f32 v122, v227, v122, 1.0
	v_fma_f32 v123, v228, v123, 1.0
	v_fma_f32 v124, v229, v124, 1.0
	v_fma_f32 v105, v230, v105, 1.0
	v_mul_f32_e64 v113, v113, -v224
	v_mul_f32_e64 v114, v114, -v225
	v_mul_f32_e64 v115, v115, -v226
	v_mul_f32_e64 v122, v122, -v227
	v_mul_f32_e64 v123, v123, -v228
	v_mul_f32_e64 v124, v124, -v229
	v_mul_f32_e64 v105, v105, -v230
	v_min3_f32 v231, v224, v225, v226
	v_min3_f32 v231, v231, v227, v228
	v_min3_f32 v231, v231, v229, v230
	v_cmp_gt_f32_e32 vcc, s72, v231
	s_cbranch_vccnz .Lp3_rare_3
; __device__ __forceinline__ float fsigmoid(float x) { return __builtin_amdgcn_rcpf(1.0f + __builtin_amdgcn_exp2f(-x * LOG2E)); }
; __device__ __forceinline__ void unpack8(u32x4 w, f32x4& a, f32x4& b) { a = (f32x4){bf_lo(w.x), bf_hi(w.x), bf_lo(w.y), bf_hi(w.y)}; b = (f32x4){bf_lo(w.z), bf_hi(w.z), bf_lo(w.w), bf_hi(w.w)}; }
; #define ST16(BASE, OFF, VAL) __builtin_amdgcn_raw_buffer_store_b128((VAL), __builtin_amdgcn_make_buffer_rsrc((void*)(BASE), (short)0, 0x7ffffff0, 0x00020000), (int)((unsigned)(OFF) * (unsigned)sizeof(*(BASE))), 0, ST_AUX)
; __device__ __forceinline__ unsigned pack_h2(float lo, float hi) { const __half2 h = __floats2half2_rn(lo, hi); return *(const unsigned*)&h; }
;     __device__ __forceinline__ void operator()(const Acc& acc, const Unit& u, int wr, int wc, int fr, int fq) const {
;     ...
;             for (int m = 0; m < 4; ++m) { const unsigned row = rowt + ai * 128 + m * 16;
;                 f32x4 x0, x1; unpack8(xw[ai * 4 + m], x0, x1);
;                 u32x4 o0, o1;
; #pragma unroll
;                 for (int h = 0; h < 2; ++h) { const f32x4 ar = acc[ai][0][m][h] + cbr[h], aiq = acc[ai][1][m][h] + cbi[h], sp = csp[h], xx = h ? x1 : x0; u32x4 o;
; #pragma unroll
;                     for (int e = 0; e < 4; ++e) { const float rr = fsigmoid(ar[e]), ii = fsigmoid(aiq[e]); const float la = -rr * sp[e], y = 2.0f * la;
;                         float m2 = -y * (1.0f + y * (0.5f + y * (0.16666667f + y * (0.041666668f + y * 0.0083333338f))));
;                         if (__builtin_expect(__any(y < -0.25f), 0)) m2 = (y < -0.25f) ? 1.0f - __builtin_amdgcn_exp2f(y * LOG2E) : m2;
;                         const float uu = ii * xx[e] * __builtin_amdgcn_sqrtf(m2); o[e] = pack_h2(la * LOG2E, uu); }
;                     if (h) o1 = o; else o0 = o; }
;                 ST16(dst, (row * 512 + ch), o0); ST16(dst, (row * 512 + ch + 4), o1); }
.Lp3_ret_3:
.LBB0_576:
	v_add_f32_e32 v100, v100, v56
	v_mul_f32_e32 v100, 0xbfb8aa3b, v100
	v_exp_f32_e32 v100, v100
	v_add_f32_e32 v101, v101, v57
	v_mul_f32_e32 v101, 0xbfb8aa3b, v101
	v_exp_f32_e32 v101, v101
	v_add_f32_e32 v100, 1.0, v100
	v_rcp_f32_e32 v100, v100
	v_sqrt_f32_e32 v122, v122
	v_add_f32_e32 v102, v102, v58
	v_lshlrev_b32_e32 v107, 16, v154
	v_mul_f32_e32 v102, 0xbfb8aa3b, v102
	v_mul_f32_e32 v100, v100, v107
	v_add_f32_e32 v101, 1.0, v101
	v_exp_f32_e32 v102, v102
	v_mul_f32_e32 v120, 0x3fb8aa3b, v120
	v_mul_f32_e32 v100, v100, v122
	v_rcp_f32_e32 v101, v101
	v_cvt_pk_f16_f32 v100, v120, v100
	v_sqrt_f32_e32 v120, v123
	v_add_f32_e32 v92, v92, v64
	v_and_b32_e32 v107, 0xffff0000, v154
	v_add_f32_e32 v102, 1.0, v102
	v_mul_f32_e32 v92, 0xbfb8aa3b, v92
	v_mul_f32_e32 v101, v101, v107
	v_rcp_f32_e32 v102, v102
	v_exp_f32_e32 v92, v92
	v_mul_f32_e32 v101, v101, v120
	v_sqrt_f32_e32 v120, v124
	v_add_f32_e32 v93, v93, v65
	v_mul_f32_e32 v107, 0x3fb8aa3b, v121
	v_mul_f32_e32 v93, 0xbfb8aa3b, v93
	v_cvt_pk_f16_f32 v101, v107, v101
	v_lshlrev_b32_e32 v107, 16, v155
	v_exp_f32_e32 v93, v93
	v_mul_f32_e32 v102, v102, v107
	v_add_f32_e32 v92, 1.0, v92
	v_mul_f32_e32 v102, v102, v120
	v_mul_f32_e32 v106, 0x3fb8aa3b, v106
	v_rcp_f32_e32 v92, v92
	v_cvt_pk_f16_f32 v102, v106, v102
	v_sqrt_f32_e32 v106, v112
	v_add_f32_e32 v93, 1.0, v93
	v_add_f32_e32 v94, v94, v66
	v_lshlrev_b32_e32 v107, 16, v152
	v_rcp_f32_e32 v93, v93
	v_mul_f32_e32 v94, 0xbfb8aa3b, v94
	v_mul_f32_e32 v92, v92, v107
	v_exp_f32_e32 v94, v94
	v_mul_f32_e32 v92, v92, v106
	v_mul_f32_e32 v106, 0x3fb8aa3b, v108
	v_cvt_pk_f16_f32 v92, v106, v92
	v_and_b32_e32 v106, 0xffff0000, v152
	v_add_f32_e32 v95, v95, v67
	v_mul_f32_e32 v93, v93, v106
	v_sqrt_f32_e32 v106, v113
	v_mul_f32_e32 v95, 0xbfb8aa3b, v95
	v_add_f32_e32 v94, 1.0, v94
	v_exp_f32_e32 v95, v95
	v_add_f32_e32 v103, v103, v59
	v_rcp_f32_e32 v94, v94
	v_mul_f32_e32 v103, 0xbfb8aa3b, v103
	v_sqrt_f32_e32 v107, v114
	v_exp_f32_e32 v103, v103
	v_mul_f32_e32 v93, v93, v106
	v_mul_f32_e32 v106, 0x3fb8aa3b, v109
	v_add_f32_e32 v80, v80, v240
	v_cvt_pk_f16_f32 v93, v106, v93
	v_lshlrev_b32_e32 v106, 16, v153
	v_add_f32_e32 v95, 1.0, v95
	v_mul_f32_e32 v80, 0xbfb8aa3b, v80
	v_mul_f32_e32 v94, v94, v106
	v_rcp_f32_e32 v95, v95
	v_exp_f32_e32 v80, v80
	v_mul_f32_e32 v94, v94, v107
	v_sqrt_f32_e32 v107, v115
	v_add_f32_e32 v103, 1.0, v103
	v_mul_f32_e32 v106, 0x3fb8aa3b, v110
	v_rcp_f32_e32 v103, v103
	v_cvt_pk_f16_f32 v94, v106, v94
	v_and_b32_e32 v106, 0xffff0000, v153
	v_mul_f32_e32 v95, v95, v106
	v_sqrt_f32_e32 v105, v105
	v_add_f32_e32 v80, 1.0, v80
	v_mul_f32_e32 v95, v95, v107
	v_mul_f32_e32 v106, 0x3fb8aa3b, v111
	v_rcp_f32_e64 v80, -v80
	v_cvt_pk_f16_f32 v95, v106, v95
	v_and_b32_e32 v106, 0xffff0000, v155
	v_mul_f32_e32 v103, v103, v106
	v_mul_f32_e32 v103, v103, v105
	v_mul_f32_e32 v104, 0x3fb8aa3b, v104
	v_cvt_pk_f16_f32 v103, v104, v103
	v_add_u32_e32 v104, 0x18000, v148
	v_mul_f32_e32 v80, v248, v80
	buffer_store_dwordx4 v[92:95], v104, s[4:7], 0 offen nt
	buffer_store_dwordx4 v[100:103], v104, s[4:7], 0 offen offset:16 nt
	s_nop 0
	v_add_f32_e32 v93, v80, v80
	v_fmamk_f32 v92, v93, 0x3c088889, v212
	v_fmaak_f32 v92, v93, v92, 0x3e2aaaab
	v_fma_f32 v92, v93, v92, 0.5
	v_fma_f32 v92, v93, v92, 1.0
	v_mul_f32_e64 v92, v92, -v93
	v_cmp_gt_f32_e32 vcc, s72, v93
	s_cbranch_vccnz .LBB0_643
.LBB0_577:
	v_add_f32_e32 v224, v81, v241
	v_add_f32_e32 v225, v82, v242
	v_add_f32_e32 v226, v83, v243
	v_add_f32_e32 v227, v68, v244
	v_add_f32_e32 v228, v69, v245
	v_add_f32_e32 v229, v70, v246
	v_add_f32_e32 v230, v71, v247
	v_mul_f32_e32 v224, 0xbfb8aa3b, v224
	v_mul_f32_e32 v225, 0xbfb8aa3b, v225
	v_mul_f32_e32 v226, 0xbfb8aa3b, v226
	v_mul_f32_e32 v227, 0xbfb8aa3b, v227
	v_mul_f32_e32 v228, 0xbfb8aa3b, v228
	v_mul_f32_e32 v229, 0xbfb8aa3b, v229
	v_mul_f32_e32 v230, 0xbfb8aa3b, v230
	v_exp_f32_e32 v224, v224
	v_exp_f32_e32 v225, v225
	v_exp_f32_e32 v226, v226
	v_exp_f32_e32 v227, v227
	v_exp_f32_e32 v228, v228
	v_exp_f32_e32 v229, v229
	v_exp_f32_e32 v230, v230
	v_add_f32_e32 v224, 1.0, v224
	v_add_f32_e32 v225, 1.0, v225
	v_add_f32_e32 v226, 1.0, v226
	v_add_f32_e32 v227, 1.0, v227
	v_add_f32_e32 v228, 1.0, v228
	v_add_f32_e32 v229, 1.0, v229
	v_add_f32_e32 v230, 1.0, v230
	v_rcp_f32_e64 v224, -v224
	v_rcp_f32_e64 v225, -v225
	v_rcp_f32_e64 v226, -v226
	v_rcp_f32_e64 v227, -v227
	v_rcp_f32_e64 v228, -v228
	v_rcp_f32_e64 v229, -v229
	v_rcp_f32_e64 v230, -v230
	v_mul_f32_e32 v81, v249, v224
	v_mul_f32_e32 v82, v250, v225
	v_mul_f32_e32 v83, v251, v226
	v_mul_f32_e32 v100, v253, v227
	v_mul_f32_e32 v101, v254, v228
	v_mul_f32_e32 v70, v255, v229
	v_mul_f32_e32 v68, v219, v230
	v_add_f32_e32 v224, v81, v81
	v_add_f32_e32 v225, v82, v82
	v_add_f32_e32 v226, v83, v83
	v_add_f32_e32 v227, v100, v100
	v_add_f32_e32 v228, v101, v101
	v_add_f32_e32 v229, v70, v70
	v_add_f32_e32 v230, v68, v68
	v_fmamk_f32 v93, v224, 0x3c088889, v212
	v_fmamk_f32 v94, v225, 0x3c088889, v212
	v_fmamk_f32 v95, v226, 0x3c088889, v212
	v_fmamk_f32 v102, v227, 0x3c088889, v212
	v_fmamk_f32 v103, v228, 0x3c088889, v212
	v_fmamk_f32 v104, v229, 0x3c088889, v212
	v_fmamk_f32 v69, v230, 0x3c088889, v212
	v_fmaak_f32 v93, v224, v93, 0x3e2aaaab
	v_fmaak_f32 v94, v225, v94, 0x3e2aaaab
	v_fmaak_f32 v95, v226, v95, 0x3e2aaaab
	v_fmaak_f32 v102, v227, v102, 0x3e2aaaab
	v_fmaak_f32 v103, v228, v103, 0x3e2aaaab
	v_fmaak_f32 v104, v229, v104, 0x3e2aaaab
	v_fmaak_f32 v69, v230, v69, 0x3e2aaaab
	v_fma_f32 v93, v224, v93, 0.5
	v_fma_f32 v94, v225, v94, 0.5
	v_fma_f32 v95, v226, v95, 0.5
	v_fma_f32 v102, v227, v102, 0.5
	v_fma_f32 v103, v228, v103, 0.5
	v_fma_f32 v104, v229, v104, 0.5
	v_fma_f32 v69, v230, v69, 0.5
	v_fma_f32 v93, v224, v93, 1.0
	v_fma_f32 v94, v225, v94, 1.0
	v_fma_f32 v95, v226, v95, 1.0
	v_fma_f32 v102, v227, v102, 1.0
	v_fma_f32 v103, v228, v103, 1.0
	v_fma_f32 v104, v229, v104, 1.0
	v_fma_f32 v69, v230, v69, 1.0
	v_mul_f32_e64 v93, v93, -v224
	v_mul_f32_e64 v94, v94, -v225
	v_mul_f32_e64 v95, v95, -v226
	v_mul_f32_e64 v102, v102, -v227
	v_mul_f32_e64 v103, v103, -v228
	v_mul_f32_e64 v104, v104, -v229
	v_mul_f32_e64 v69, v69, -v230
	v_min3_f32 v231, v224, v225, v226
	v_min3_f32 v231, v231, v227, v228
	v_min3_f32 v231, v231, v229, v230
	v_cmp_gt_f32_e32 vcc, s72, v231
	s_cbranch_vccnz .Lp3_rare_4
; __device__ __forceinline__ float fsigmoid(float x) { return __builtin_amdgcn_rcpf(1.0f + __builtin_amdgcn_exp2f(-x * LOG2E)); }
; __device__ __forceinline__ void unpack8(u32x4 w, f32x4& a, f32x4& b) { a = (f32x4){bf_lo(w.x), bf_hi(w.x), bf_lo(w.y), bf_hi(w.y)}; b = (f32x4){bf_lo(w.z), bf_hi(w.z), bf_lo(w.w), bf_hi(w.w)}; }
; #define ST16(BASE, OFF, VAL) __builtin_amdgcn_raw_buffer_store_b128((VAL), __builtin_amdgcn_make_buffer_rsrc((void*)(BASE), (short)0, 0x7ffffff0, 0x00020000), (int)((unsigned)(OFF) * (unsigned)sizeof(*(BASE))), 0, ST_AUX)
; __device__ __forceinline__ unsigned pack_h2(float lo, float hi) { const __half2 h = __floats2half2_rn(lo, hi); return *(const unsigned*)&h; }
;     __device__ __forceinline__ void operator()(const Acc& acc, const Unit& u, int wr, int wc, int fr, int fq) const {
;     ...
;             for (int m = 0; m < 4; ++m) { const unsigned row = rowt + ai * 128 + m * 16;
;                 f32x4 x0, x1; unpack8(xw[ai * 4 + m], x0, x1);
;                 u32x4 o0, o1;
; #pragma unroll
;                 for (int h = 0; h < 2; ++h) { const f32x4 ar = acc[ai][0][m][h] + cbr[h], aiq = acc[ai][1][m][h] + cbi[h], sp = csp[h], xx = h ? x1 : x0; u32x4 o;
; #pragma unroll
;                     for (int e = 0; e < 4; ++e) { const float rr = fsigmoid(ar[e]), ii = fsigmoid(aiq[e]); const float la = -rr * sp[e], y = 2.0f * la;
;                         float m2 = -y * (1.0f + y * (0.5f + y * (0.16666667f + y * (0.041666668f + y * 0.0083333338f))));
;                         if (__builtin_expect(__any(y < -0.25f), 0)) m2 = (y < -0.25f) ? 1.0f - __builtin_amdgcn_exp2f(y * LOG2E) : m2;
;                         const float uu = ii * xx[e] * __builtin_amdgcn_sqrtf(m2); o[e] = pack_h2(la * LOG2E, uu); }
;                     if (h) o1 = o; else o0 = o; }
;                 ST16(dst, (row * 512 + ch), o0); ST16(dst, (row * 512 + ch + 4), o1); }
.Lp3_ret_4:
.LBB0_584:
	v_add_f32_e32 v60, v60, v56
	v_mul_f32_e32 v60, 0xbfb8aa3b, v60
	v_exp_f32_e32 v60, v60
	v_add_f32_e32 v61, v61, v57
	v_mul_f32_e32 v61, 0xbfb8aa3b, v61
	v_exp_f32_e32 v61, v61
	v_add_f32_e32 v60, 1.0, v60
	v_rcp_f32_e32 v60, v60
	v_sqrt_f32_e32 v102, v102
	v_add_f32_e32 v62, v62, v58
	v_lshlrev_b32_e32 v71, 16, v138
	v_mul_f32_e32 v62, 0xbfb8aa3b, v62
	v_mul_f32_e32 v60, v60, v71
	v_add_f32_e32 v61, 1.0, v61
	v_exp_f32_e32 v62, v62
	v_mul_f32_e32 v100, 0x3fb8aa3b, v100
	v_mul_f32_e32 v60, v60, v102
	v_rcp_f32_e32 v61, v61
	v_cvt_pk_f16_f32 v60, v100, v60
	v_sqrt_f32_e32 v100, v103
	v_add_f32_e32 v48, v48, v64
	v_and_b32_e32 v71, 0xffff0000, v138
	v_add_f32_e32 v62, 1.0, v62
	v_mul_f32_e32 v48, 0xbfb8aa3b, v48
	v_mul_f32_e32 v61, v61, v71
	v_rcp_f32_e32 v62, v62
	v_exp_f32_e32 v48, v48
	v_mul_f32_e32 v61, v61, v100
	v_sqrt_f32_e32 v100, v104
	v_add_f32_e32 v49, v49, v65
	v_mul_f32_e32 v71, 0x3fb8aa3b, v101
	v_mul_f32_e32 v49, 0xbfb8aa3b, v49
	v_cvt_pk_f16_f32 v61, v71, v61
	v_lshlrev_b32_e32 v71, 16, v139
	v_exp_f32_e32 v49, v49
	v_mul_f32_e32 v62, v62, v71
	v_add_f32_e32 v48, 1.0, v48
	v_mul_f32_e32 v62, v62, v100
	v_mul_f32_e32 v70, 0x3fb8aa3b, v70
	v_rcp_f32_e32 v48, v48
	v_cvt_pk_f16_f32 v62, v70, v62
	v_sqrt_f32_e32 v70, v92
	v_add_f32_e32 v49, 1.0, v49
	v_add_f32_e32 v50, v50, v66
	v_lshlrev_b32_e32 v71, 16, v136
	v_rcp_f32_e32 v49, v49
	v_mul_f32_e32 v50, 0xbfb8aa3b, v50
	v_mul_f32_e32 v48, v48, v71
	v_exp_f32_e32 v50, v50
	v_mul_f32_e32 v48, v48, v70
	v_mul_f32_e32 v70, 0x3fb8aa3b, v80
	v_cvt_pk_f16_f32 v48, v70, v48
	v_and_b32_e32 v70, 0xffff0000, v136
	v_add_f32_e32 v51, v51, v67
	v_mul_f32_e32 v49, v49, v70
	v_sqrt_f32_e32 v70, v93
	v_mul_f32_e32 v51, 0xbfb8aa3b, v51
	v_add_f32_e32 v50, 1.0, v50
	v_exp_f32_e32 v51, v51
	v_add_f32_e32 v63, v63, v59
	v_rcp_f32_e32 v50, v50
	v_mul_f32_e32 v63, 0xbfb8aa3b, v63
	v_sqrt_f32_e32 v71, v94
	v_exp_f32_e32 v63, v63
	v_mul_f32_e32 v49, v49, v70
	v_mul_f32_e32 v70, 0x3fb8aa3b, v81
	v_add_f32_e32 v44, v44, v240
	v_cvt_pk_f16_f32 v49, v70, v49
	v_lshlrev_b32_e32 v70, 16, v137
	v_add_f32_e32 v51, 1.0, v51
	v_mul_f32_e32 v44, 0xbfb8aa3b, v44
	v_mul_f32_e32 v50, v50, v70
	v_rcp_f32_e32 v51, v51
	v_exp_f32_e32 v44, v44
	v_mul_f32_e32 v50, v50, v71
	v_sqrt_f32_e32 v71, v95
	v_add_f32_e32 v63, 1.0, v63
	v_mul_f32_e32 v70, 0x3fb8aa3b, v82
	v_rcp_f32_e32 v63, v63
	v_cvt_pk_f16_f32 v50, v70, v50
	v_and_b32_e32 v70, 0xffff0000, v137
	v_mul_f32_e32 v51, v51, v70
	v_sqrt_f32_e32 v69, v69
	v_add_f32_e32 v44, 1.0, v44
	v_mul_f32_e32 v51, v51, v71
	v_mul_f32_e32 v70, 0x3fb8aa3b, v83
	v_rcp_f32_e64 v44, -v44
	v_cvt_pk_f16_f32 v51, v70, v51
	v_and_b32_e32 v70, 0xffff0000, v139
	v_mul_f32_e32 v63, v63, v70
	v_mul_f32_e32 v63, v63, v69
	v_mul_f32_e32 v68, 0x3fb8aa3b, v68
	v_cvt_pk_f16_f32 v63, v68, v63
	v_add_u32_e32 v68, 0x40000, v148
	v_mul_f32_e32 v44, v248, v44
	buffer_store_dwordx4 v[48:51], v68, s[4:7], 0 offen nt
	buffer_store_dwordx4 v[60:63], v68, s[4:7], 0 offen offset:16 nt
	s_nop 0
	v_add_f32_e32 v49, v44, v44
	v_fmamk_f32 v48, v49, 0x3c088889, v212
	v_fmaak_f32 v48, v49, v48, 0x3e2aaaab
	v_fma_f32 v48, v49, v48, 0.5
	v_fma_f32 v48, v49, v48, 1.0
	v_mul_f32_e64 v48, v48, -v49
	v_cmp_gt_f32_e32 vcc, s72, v49
	s_cbranch_vccnz .LBB0_651
.LBB0_585:
	v_add_f32_e32 v224, v45, v241
	v_add_f32_e32 v225, v46, v242
	v_add_f32_e32 v226, v47, v243
	v_add_f32_e32 v227, v40, v244
	v_add_f32_e32 v228, v41, v245
	v_add_f32_e32 v229, v42, v246
	v_add_f32_e32 v230, v43, v247
	v_mul_f32_e32 v224, 0xbfb8aa3b, v224
	v_mul_f32_e32 v225, 0xbfb8aa3b, v225
	v_mul_f32_e32 v226, 0xbfb8aa3b, v226
	v_mul_f32_e32 v227, 0xbfb8aa3b, v227
	v_mul_f32_e32 v228, 0xbfb8aa3b, v228
	v_mul_f32_e32 v229, 0xbfb8aa3b, v229
	v_mul_f32_e32 v230, 0xbfb8aa3b, v230
	v_exp_f32_e32 v224, v224
	v_exp_f32_e32 v225, v225
	v_exp_f32_e32 v226, v226
	v_exp_f32_e32 v227, v227
	v_exp_f32_e32 v228, v228
	v_exp_f32_e32 v229, v229
	v_exp_f32_e32 v230, v230
	v_add_f32_e32 v224, 1.0, v224
	v_add_f32_e32 v225, 1.0, v225
	v_add_f32_e32 v226, 1.0, v226
	v_add_f32_e32 v227, 1.0, v227
	v_add_f32_e32 v228, 1.0, v228
	v_add_f32_e32 v229, 1.0, v229
	v_add_f32_e32 v230, 1.0, v230
	v_rcp_f32_e64 v224, -v224
	v_rcp_f32_e64 v225, -v225
	v_rcp_f32_e64 v226, -v226
	v_rcp_f32_e64 v227, -v227
	v_rcp_f32_e64 v228, -v228
	v_rcp_f32_e64 v229, -v229
	v_rcp_f32_e64 v230, -v230
	v_mul_f32_e32 v45, v249, v224
	v_mul_f32_e32 v46, v250, v225
	v_mul_f32_e32 v47, v251, v226
	v_mul_f32_e32 v60, v253, v227
	v_mul_f32_e32 v61, v254, v228
	v_mul_f32_e32 v42, v255, v229
	v_mul_f32_e32 v40, v219, v230
	v_add_f32_e32 v224, v45, v45
	v_add_f32_e32 v225, v46, v46
	v_add_f32_e32 v226, v47, v47
	v_add_f32_e32 v227, v60, v60
	v_add_f32_e32 v228, v61, v61
	v_add_f32_e32 v229, v42, v42
	v_add_f32_e32 v230, v40, v40
	v_fmamk_f32 v49, v224, 0x3c088889, v212
	v_fmamk_f32 v50, v225, 0x3c088889, v212
	v_fmamk_f32 v51, v226, 0x3c088889, v212
	v_fmamk_f32 v62, v227, 0x3c088889, v212
	v_fmamk_f32 v63, v228, 0x3c088889, v212
	v_fmamk_f32 v68, v229, 0x3c088889, v212
	v_fmamk_f32 v41, v230, 0x3c088889, v212
	v_fmaak_f32 v49, v224, v49, 0x3e2aaaab
	v_fmaak_f32 v50, v225, v50, 0x3e2aaaab
	v_fmaak_f32 v51, v226, v51, 0x3e2aaaab
	v_fmaak_f32 v62, v227, v62, 0x3e2aaaab
	v_fmaak_f32 v63, v228, v63, 0x3e2aaaab
	v_fmaak_f32 v68, v229, v68, 0x3e2aaaab
	v_fmaak_f32 v41, v230, v41, 0x3e2aaaab
	v_fma_f32 v49, v224, v49, 0.5
	v_fma_f32 v50, v225, v50, 0.5
	v_fma_f32 v51, v226, v51, 0.5
	v_fma_f32 v62, v227, v62, 0.5
	v_fma_f32 v63, v228, v63, 0.5
	v_fma_f32 v68, v229, v68, 0.5
	v_fma_f32 v41, v230, v41, 0.5
	v_fma_f32 v49, v224, v49, 1.0
	v_fma_f32 v50, v225, v50, 1.0
	v_fma_f32 v51, v226, v51, 1.0
	v_fma_f32 v62, v227, v62, 1.0
	v_fma_f32 v63, v228, v63, 1.0
	v_fma_f32 v68, v229, v68, 1.0
	v_fma_f32 v41, v230, v41, 1.0
	v_mul_f32_e64 v49, v49, -v224
	v_mul_f32_e64 v50, v50, -v225
	v_mul_f32_e64 v51, v51, -v226
	v_mul_f32_e64 v62, v62, -v227
	v_mul_f32_e64 v63, v63, -v228
	v_mul_f32_e64 v68, v68, -v229
	v_mul_f32_e64 v41, v41, -v230
	v_min3_f32 v231, v224, v225, v226
	v_min3_f32 v231, v231, v227, v228
	v_min3_f32 v231, v231, v229, v230
	v_cmp_gt_f32_e32 vcc, s72, v231
	s_cbranch_vccnz .Lp3_rare_5
; __device__ __forceinline__ float fsigmoid(float x) { return __builtin_amdgcn_rcpf(1.0f + __builtin_amdgcn_exp2f(-x * LOG2E)); }
; __device__ __forceinline__ void unpack8(u32x4 w, f32x4& a, f32x4& b) { a = (f32x4){bf_lo(w.x), bf_hi(w.x), bf_lo(w.y), bf_hi(w.y)}; b = (f32x4){bf_lo(w.z), bf_hi(w.z), bf_lo(w.w), bf_hi(w.w)}; }
; #define ST16(BASE, OFF, VAL) __builtin_amdgcn_raw_buffer_store_b128((VAL), __builtin_amdgcn_make_buffer_rsrc((void*)(BASE), (short)0, 0x7ffffff0, 0x00020000), (int)((unsigned)(OFF) * (unsigned)sizeof(*(BASE))), 0, ST_AUX)
; __device__ __forceinline__ unsigned pack_h2(float lo, float hi) { const __half2 h = __floats2half2_rn(lo, hi); return *(const unsigned*)&h; }
;     __device__ __forceinline__ void operator()(const Acc& acc, const Unit& u, int wr, int wc, int fr, int fq) const {
;     ...
;             for (int m = 0; m < 4; ++m) { const unsigned row = rowt + ai * 128 + m * 16;
;                 f32x4 x0, x1; unpack8(xw[ai * 4 + m], x0, x1);
;                 u32x4 o0, o1;
; #pragma unroll
;                 for (int h = 0; h < 2; ++h) { const f32x4 ar = acc[ai][0][m][h] + cbr[h], aiq = acc[ai][1][m][h] + cbi[h], sp = csp[h], xx = h ? x1 : x0; u32x4 o;
; #pragma unroll
;                     for (int e = 0; e < 4; ++e) { const float rr = fsigmoid(ar[e]), ii = fsigmoid(aiq[e]); const float la = -rr * sp[e], y = 2.0f * la;
;                         float m2 = -y * (1.0f + y * (0.5f + y * (0.16666667f + y * (0.041666668f + y * 0.0083333338f))));
;                         if (__builtin_expect(__any(y < -0.25f), 0)) m2 = (y < -0.25f) ? 1.0f - __builtin_amdgcn_exp2f(y * LOG2E) : m2;
;                         const float uu = ii * xx[e] * __builtin_amdgcn_sqrtf(m2); o[e] = pack_h2(la * LOG2E, uu); }
;                     if (h) o1 = o; else o0 = o; }
;                 ST16(dst, (row * 512 + ch), o0); ST16(dst, (row * 512 + ch + 4), o1); }
.Lp3_ret_5:
.LBB0_592:
	v_add_f32_e32 v36, v36, v56
	v_mul_f32_e32 v36, 0xbfb8aa3b, v36
	v_exp_f32_e32 v36, v36
	v_add_f32_e32 v37, v37, v57
	v_mul_f32_e32 v37, 0xbfb8aa3b, v37
	v_exp_f32_e32 v37, v37
	v_add_f32_e32 v36, 1.0, v36
	v_rcp_f32_e32 v36, v36
	v_sqrt_f32_e32 v62, v62
	v_add_f32_e32 v38, v38, v58
	v_lshlrev_b32_e32 v43, 16, v118
	v_mul_f32_e32 v38, 0xbfb8aa3b, v38
	v_mul_f32_e32 v36, v36, v43
	v_add_f32_e32 v37, 1.0, v37
	v_exp_f32_e32 v38, v38
	v_mul_f32_e32 v60, 0x3fb8aa3b, v60
	v_mul_f32_e32 v36, v36, v62
	v_rcp_f32_e32 v37, v37
	v_cvt_pk_f16_f32 v36, v60, v36
	v_sqrt_f32_e32 v60, v63
	v_add_f32_e32 v32, v32, v64
	v_and_b32_e32 v43, 0xffff0000, v118
	v_add_f32_e32 v38, 1.0, v38
	v_mul_f32_e32 v32, 0xbfb8aa3b, v32
	v_mul_f32_e32 v37, v37, v43
	v_rcp_f32_e32 v38, v38
	v_exp_f32_e32 v32, v32
	v_mul_f32_e32 v37, v37, v60
	v_sqrt_f32_e32 v60, v68
	v_add_f32_e32 v33, v33, v65
	v_mul_f32_e32 v43, 0x3fb8aa3b, v61
	v_mul_f32_e32 v33, 0xbfb8aa3b, v33
	v_cvt_pk_f16_f32 v37, v43, v37
	v_lshlrev_b32_e32 v43, 16, v119
	v_exp_f32_e32 v33, v33
	v_mul_f32_e32 v38, v38, v43
	v_add_f32_e32 v32, 1.0, v32
	v_mul_f32_e32 v38, v38, v60
	v_mul_f32_e32 v42, 0x3fb8aa3b, v42
	v_rcp_f32_e32 v32, v32
	v_cvt_pk_f16_f32 v38, v42, v38
	v_sqrt_f32_e32 v42, v48
	v_add_f32_e32 v33, 1.0, v33
	v_add_f32_e32 v34, v34, v66
	v_lshlrev_b32_e32 v43, 16, v116
	v_rcp_f32_e32 v33, v33
	v_mul_f32_e32 v34, 0xbfb8aa3b, v34
	v_mul_f32_e32 v32, v32, v43
	v_exp_f32_e32 v34, v34
	v_mul_f32_e32 v32, v32, v42
	v_mul_f32_e32 v42, 0x3fb8aa3b, v44
	v_cvt_pk_f16_f32 v32, v42, v32
	v_and_b32_e32 v42, 0xffff0000, v116
	v_add_f32_e32 v35, v35, v67
	v_mul_f32_e32 v33, v33, v42
	v_sqrt_f32_e32 v42, v49
	v_mul_f32_e32 v35, 0xbfb8aa3b, v35
	v_add_f32_e32 v34, 1.0, v34
	v_exp_f32_e32 v35, v35
	v_add_f32_e32 v39, v39, v59
	v_rcp_f32_e32 v34, v34
	v_mul_f32_e32 v39, 0xbfb8aa3b, v39
	v_sqrt_f32_e32 v43, v50
	v_exp_f32_e32 v39, v39
	v_mul_f32_e32 v33, v33, v42
	v_mul_f32_e32 v42, 0x3fb8aa3b, v45
	v_add_f32_e32 v28, v28, v240
	v_cvt_pk_f16_f32 v33, v42, v33
	v_lshlrev_b32_e32 v42, 16, v117
	v_add_f32_e32 v35, 1.0, v35
	v_mul_f32_e32 v28, 0xbfb8aa3b, v28
	v_mul_f32_e32 v34, v34, v42
	v_rcp_f32_e32 v35, v35
	v_exp_f32_e32 v28, v28
	v_mul_f32_e32 v34, v34, v43
	v_sqrt_f32_e32 v43, v51
	v_add_f32_e32 v39, 1.0, v39
	v_mul_f32_e32 v42, 0x3fb8aa3b, v46
	v_rcp_f32_e32 v39, v39
	v_cvt_pk_f16_f32 v34, v42, v34
	v_and_b32_e32 v42, 0xffff0000, v117
	v_mul_f32_e32 v35, v35, v42
	v_sqrt_f32_e32 v41, v41
	v_add_f32_e32 v28, 1.0, v28
	v_mul_f32_e32 v35, v35, v43
	v_mul_f32_e32 v42, 0x3fb8aa3b, v47
	v_rcp_f32_e64 v28, -v28
	v_cvt_pk_f16_f32 v35, v42, v35
	v_and_b32_e32 v42, 0xffff0000, v119
	v_mul_f32_e32 v39, v39, v42
	v_mul_f32_e32 v39, v39, v41
	v_mul_f32_e32 v40, 0x3fb8aa3b, v40
	v_cvt_pk_f16_f32 v39, v40, v39
	v_add_u32_e32 v40, 0x48000, v148
	v_mul_f32_e32 v28, v248, v28
	buffer_store_dwordx4 v[32:35], v40, s[4:7], 0 offen nt
	buffer_store_dwordx4 v[36:39], v40, s[4:7], 0 offen offset:16 nt
	s_nop 0
	v_add_f32_e32 v33, v28, v28
	v_fmamk_f32 v32, v33, 0x3c088889, v212
	v_fmaak_f32 v32, v33, v32, 0x3e2aaaab
	v_fma_f32 v32, v33, v32, 0.5
	v_fma_f32 v32, v33, v32, 1.0
	v_mul_f32_e64 v32, v32, -v33
	v_cmp_gt_f32_e32 vcc, s72, v33
	s_cbranch_vccnz .LBB0_659
.LBB0_593:
	v_add_f32_e32 v224, v29, v241
	v_add_f32_e32 v225, v30, v242
	v_add_f32_e32 v226, v31, v243
	v_add_f32_e32 v227, v24, v244
	v_add_f32_e32 v228, v25, v245
	v_add_f32_e32 v229, v26, v246
	v_add_f32_e32 v230, v27, v247
	v_mul_f32_e32 v224, 0xbfb8aa3b, v224
	v_mul_f32_e32 v225, 0xbfb8aa3b, v225
	v_mul_f32_e32 v226, 0xbfb8aa3b, v226
	v_mul_f32_e32 v227, 0xbfb8aa3b, v227
	v_mul_f32_e32 v228, 0xbfb8aa3b, v228
	v_mul_f32_e32 v229, 0xbfb8aa3b, v229
	v_mul_f32_e32 v230, 0xbfb8aa3b, v230
	v_exp_f32_e32 v224, v224
	v_exp_f32_e32 v225, v225
	v_exp_f32_e32 v226, v226
	v_exp_f32_e32 v227, v227
	v_exp_f32_e32 v228, v228
	v_exp_f32_e32 v229, v229
	v_exp_f32_e32 v230, v230
	v_add_f32_e32 v224, 1.0, v224
	v_add_f32_e32 v225, 1.0, v225
	v_add_f32_e32 v226, 1.0, v226
	v_add_f32_e32 v227, 1.0, v227
	v_add_f32_e32 v228, 1.0, v228
	v_add_f32_e32 v229, 1.0, v229
	v_add_f32_e32 v230, 1.0, v230
	v_rcp_f32_e64 v224, -v224
	v_rcp_f32_e64 v225, -v225
	v_rcp_f32_e64 v226, -v226
	v_rcp_f32_e64 v227, -v227
	v_rcp_f32_e64 v228, -v228
	v_rcp_f32_e64 v229, -v229
	v_rcp_f32_e64 v230, -v230
	v_mul_f32_e32 v29, v249, v224
	v_mul_f32_e32 v30, v250, v225
	v_mul_f32_e32 v31, v251, v226
	v_mul_f32_e32 v36, v253, v227
	v_mul_f32_e32 v37, v254, v228
	v_mul_f32_e32 v26, v255, v229
	v_mul_f32_e32 v24, v219, v230
	v_add_f32_e32 v224, v29, v29
	v_add_f32_e32 v225, v30, v30
	v_add_f32_e32 v226, v31, v31
	v_add_f32_e32 v227, v36, v36
	v_add_f32_e32 v228, v37, v37
	v_add_f32_e32 v229, v26, v26
	v_add_f32_e32 v230, v24, v24
	v_fmamk_f32 v33, v224, 0x3c088889, v212
	v_fmamk_f32 v34, v225, 0x3c088889, v212
	v_fmamk_f32 v35, v226, 0x3c088889, v212
	v_fmamk_f32 v38, v227, 0x3c088889, v212
	v_fmamk_f32 v39, v228, 0x3c088889, v212
	v_fmamk_f32 v40, v229, 0x3c088889, v212
	v_fmamk_f32 v25, v230, 0x3c088889, v212
	v_fmaak_f32 v33, v224, v33, 0x3e2aaaab
	v_fmaak_f32 v34, v225, v34, 0x3e2aaaab
	v_fmaak_f32 v35, v226, v35, 0x3e2aaaab
	v_fmaak_f32 v38, v227, v38, 0x3e2aaaab
	v_fmaak_f32 v39, v228, v39, 0x3e2aaaab
	v_fmaak_f32 v40, v229, v40, 0x3e2aaaab
	v_fmaak_f32 v25, v230, v25, 0x3e2aaaab
	v_fma_f32 v33, v224, v33, 0.5
	v_fma_f32 v34, v225, v34, 0.5
	v_fma_f32 v35, v226, v35, 0.5
	v_fma_f32 v38, v227, v38, 0.5
	v_fma_f32 v39, v228, v39, 0.5
	v_fma_f32 v40, v229, v40, 0.5
	v_fma_f32 v25, v230, v25, 0.5
	v_fma_f32 v33, v224, v33, 1.0
	v_fma_f32 v34, v225, v34, 1.0
	v_fma_f32 v35, v226, v35, 1.0
	v_fma_f32 v38, v227, v38, 1.0
	v_fma_f32 v39, v228, v39, 1.0
	v_fma_f32 v40, v229, v40, 1.0
	v_fma_f32 v25, v230, v25, 1.0
	v_mul_f32_e64 v33, v33, -v224
	v_mul_f32_e64 v34, v34, -v225
	v_mul_f32_e64 v35, v35, -v226
	v_mul_f32_e64 v38, v38, -v227
	v_mul_f32_e64 v39, v39, -v228
	v_mul_f32_e64 v40, v40, -v229
	v_mul_f32_e64 v25, v25, -v230
	v_min3_f32 v231, v224, v225, v226
	v_min3_f32 v231, v231, v227, v228
	v_min3_f32 v231, v231, v229, v230
	v_cmp_gt_f32_e32 vcc, s72, v231
	s_cbranch_vccnz .Lp3_rare_6
; __device__ __forceinline__ float fsigmoid(float x) { return __builtin_amdgcn_rcpf(1.0f + __builtin_amdgcn_exp2f(-x * LOG2E)); }
; __device__ __forceinline__ void unpack8(u32x4 w, f32x4& a, f32x4& b) { a = (f32x4){bf_lo(w.x), bf_hi(w.x), bf_lo(w.y), bf_hi(w.y)}; b = (f32x4){bf_lo(w.z), bf_hi(w.z), bf_lo(w.w), bf_hi(w.w)}; }
; #define ST16(BASE, OFF, VAL) __builtin_amdgcn_raw_buffer_store_b128((VAL), __builtin_amdgcn_make_buffer_rsrc((void*)(BASE), (short)0, 0x7ffffff0, 0x00020000), (int)((unsigned)(OFF) * (unsigned)sizeof(*(BASE))), 0, ST_AUX)
; __device__ __forceinline__ unsigned pack_h2(float lo, float hi) { const __half2 h = __floats2half2_rn(lo, hi); return *(const unsigned*)&h; }
;     __device__ __forceinline__ void operator()(const Acc& acc, const Unit& u, int wr, int wc, int fr, int fq) const {
;     ...
;             for (int m = 0; m < 4; ++m) { const unsigned row = rowt + ai * 128 + m * 16;
;                 f32x4 x0, x1; unpack8(xw[ai * 4 + m], x0, x1);
;                 u32x4 o0, o1;
; #pragma unroll
;                 for (int h = 0; h < 2; ++h) { const f32x4 ar = acc[ai][0][m][h] + cbr[h], aiq = acc[ai][1][m][h] + cbi[h], sp = csp[h], xx = h ? x1 : x0; u32x4 o;
; #pragma unroll
;                     for (int e = 0; e < 4; ++e) { const float rr = fsigmoid(ar[e]), ii = fsigmoid(aiq[e]); const float la = -rr * sp[e], y = 2.0f * la;
;                         float m2 = -y * (1.0f + y * (0.5f + y * (0.16666667f + y * (0.041666668f + y * 0.0083333338f))));
;                         if (__builtin_expect(__any(y < -0.25f), 0)) m2 = (y < -0.25f) ? 1.0f - __builtin_amdgcn_exp2f(y * LOG2E) : m2;
;                         const float uu = ii * xx[e] * __builtin_amdgcn_sqrtf(m2); o[e] = pack_h2(la * LOG2E, uu); }
;                     if (h) o1 = o; else o0 = o; }
;                 ST16(dst, (row * 512 + ch), o0); ST16(dst, (row * 512 + ch + 4), o1); }
.Lp3_ret_6:
.LBB0_600:
	v_add_f32_e32 v20, v20, v56
	v_mul_f32_e32 v20, 0xbfb8aa3b, v20
	v_exp_f32_e32 v20, v20
	v_add_f32_e32 v21, v21, v57
	v_mul_f32_e32 v21, 0xbfb8aa3b, v21
	v_exp_f32_e32 v21, v21
	v_add_f32_e32 v20, 1.0, v20
	v_rcp_f32_e32 v20, v20
	v_sqrt_f32_e32 v38, v38
	v_add_f32_e32 v22, v22, v58
	v_lshlrev_b32_e32 v27, 16, v98
	v_mul_f32_e32 v22, 0xbfb8aa3b, v22
	v_mul_f32_e32 v20, v20, v27
	v_add_f32_e32 v21, 1.0, v21
	v_exp_f32_e32 v22, v22
	v_mul_f32_e32 v36, 0x3fb8aa3b, v36
	v_mul_f32_e32 v20, v20, v38
	v_rcp_f32_e32 v21, v21
	v_cvt_pk_f16_f32 v20, v36, v20
	v_sqrt_f32_e32 v36, v39
	v_add_f32_e32 v16, v16, v64
	v_and_b32_e32 v27, 0xffff0000, v98
	v_add_f32_e32 v22, 1.0, v22
	v_mul_f32_e32 v16, 0xbfb8aa3b, v16
	v_mul_f32_e32 v21, v21, v27
	v_rcp_f32_e32 v22, v22
	v_exp_f32_e32 v16, v16
	v_mul_f32_e32 v21, v21, v36
	v_sqrt_f32_e32 v36, v40
	v_add_f32_e32 v17, v17, v65
	v_mul_f32_e32 v27, 0x3fb8aa3b, v37
	v_mul_f32_e32 v17, 0xbfb8aa3b, v17
	v_cvt_pk_f16_f32 v21, v27, v21
	v_lshlrev_b32_e32 v27, 16, v99
	v_exp_f32_e32 v17, v17
	v_mul_f32_e32 v22, v22, v27
	v_add_f32_e32 v16, 1.0, v16
	v_mul_f32_e32 v22, v22, v36
	v_mul_f32_e32 v26, 0x3fb8aa3b, v26
	v_rcp_f32_e32 v16, v16
	v_cvt_pk_f16_f32 v22, v26, v22
	v_sqrt_f32_e32 v26, v32
	v_add_f32_e32 v17, 1.0, v17
	v_add_f32_e32 v18, v18, v66
	v_lshlrev_b32_e32 v27, 16, v96
	v_rcp_f32_e32 v17, v17
	v_mul_f32_e32 v18, 0xbfb8aa3b, v18
	v_mul_f32_e32 v16, v16, v27
	v_exp_f32_e32 v18, v18
	v_mul_f32_e32 v16, v16, v26
	v_mul_f32_e32 v26, 0x3fb8aa3b, v28
	v_cvt_pk_f16_f32 v16, v26, v16
	v_and_b32_e32 v26, 0xffff0000, v96
	v_add_f32_e32 v19, v19, v67
	v_mul_f32_e32 v17, v17, v26
	v_sqrt_f32_e32 v26, v33
	v_mul_f32_e32 v19, 0xbfb8aa3b, v19
	v_add_f32_e32 v18, 1.0, v18
	v_exp_f32_e32 v19, v19
	v_add_f32_e32 v23, v23, v59
	v_rcp_f32_e32 v18, v18
	v_mul_f32_e32 v23, 0xbfb8aa3b, v23
	v_sqrt_f32_e32 v27, v34
	v_exp_f32_e32 v23, v23
	v_mul_f32_e32 v17, v17, v26
	v_mul_f32_e32 v26, 0x3fb8aa3b, v29
	v_add_f32_e32 v12, v12, v240
	v_cvt_pk_f16_f32 v17, v26, v17
	v_lshlrev_b32_e32 v26, 16, v97
	v_add_f32_e32 v19, 1.0, v19
	v_mul_f32_e32 v12, 0xbfb8aa3b, v12
	v_mul_f32_e32 v18, v18, v26
	v_rcp_f32_e32 v19, v19
	v_exp_f32_e32 v12, v12
	v_mul_f32_e32 v18, v18, v27
	v_sqrt_f32_e32 v27, v35
	v_add_f32_e32 v23, 1.0, v23
	v_mul_f32_e32 v26, 0x3fb8aa3b, v30
	v_rcp_f32_e32 v23, v23
	v_cvt_pk_f16_f32 v18, v26, v18
	v_and_b32_e32 v26, 0xffff0000, v97
	v_mul_f32_e32 v19, v19, v26
	v_sqrt_f32_e32 v25, v25
	v_add_f32_e32 v12, 1.0, v12
	v_mul_f32_e32 v19, v19, v27
	v_mul_f32_e32 v26, 0x3fb8aa3b, v31
	v_rcp_f32_e64 v12, -v12
	v_cvt_pk_f16_f32 v19, v26, v19
	v_and_b32_e32 v26, 0xffff0000, v99
	v_mul_f32_e32 v23, v23, v26
	v_mul_f32_e32 v23, v23, v25
	v_mul_f32_e32 v24, 0x3fb8aa3b, v24
	v_cvt_pk_f16_f32 v23, v24, v23
	v_add_u32_e32 v24, 0x50000, v148
	v_mul_f32_e32 v12, v248, v12
	buffer_store_dwordx4 v[16:19], v24, s[4:7], 0 offen nt
	buffer_store_dwordx4 v[20:23], v24, s[4:7], 0 offen offset:16 nt
	s_nop 0
	v_add_f32_e32 v17, v12, v12
	v_fmamk_f32 v16, v17, 0x3c088889, v212
	v_fmaak_f32 v16, v17, v16, 0x3e2aaaab
	v_fma_f32 v16, v17, v16, 0.5
	v_fma_f32 v16, v17, v16, 1.0
	v_mul_f32_e64 v16, v16, -v17
	v_cmp_gt_f32_e32 vcc, s72, v17
	s_cbranch_vccnz .LBB0_667
.LBB0_601:
	v_add_f32_e32 v224, v13, v241
	v_add_f32_e32 v225, v14, v242
	v_add_f32_e32 v226, v15, v243
	v_add_f32_e32 v227, v8, v244
	v_add_f32_e32 v228, v9, v245
	v_add_f32_e32 v229, v10, v246
	v_add_f32_e32 v230, v11, v247
	v_mul_f32_e32 v224, 0xbfb8aa3b, v224
	v_mul_f32_e32 v225, 0xbfb8aa3b, v225
	v_mul_f32_e32 v226, 0xbfb8aa3b, v226
	v_mul_f32_e32 v227, 0xbfb8aa3b, v227
	v_mul_f32_e32 v228, 0xbfb8aa3b, v228
	v_mul_f32_e32 v229, 0xbfb8aa3b, v229
	v_mul_f32_e32 v230, 0xbfb8aa3b, v230
	v_exp_f32_e32 v224, v224
	v_exp_f32_e32 v225, v225
	v_exp_f32_e32 v226, v226
	v_exp_f32_e32 v227, v227
	v_exp_f32_e32 v228, v228
	v_exp_f32_e32 v229, v229
	v_exp_f32_e32 v230, v230
	v_add_f32_e32 v224, 1.0, v224
	v_add_f32_e32 v225, 1.0, v225
	v_add_f32_e32 v226, 1.0, v226
	v_add_f32_e32 v227, 1.0, v227
	v_add_f32_e32 v228, 1.0, v228
	v_add_f32_e32 v229, 1.0, v229
	v_add_f32_e32 v230, 1.0, v230
	v_rcp_f32_e64 v224, -v224
	v_rcp_f32_e64 v225, -v225
	v_rcp_f32_e64 v226, -v226
	v_rcp_f32_e64 v227, -v227
	v_rcp_f32_e64 v228, -v228
	v_rcp_f32_e64 v229, -v229
	v_rcp_f32_e64 v230, -v230
	v_mul_f32_e32 v13, v249, v224
	v_mul_f32_e32 v14, v250, v225
	v_mul_f32_e32 v15, v251, v226
	v_mul_f32_e32 v8, v253, v227
	v_mul_f32_e32 v9, v254, v228
	v_mul_f32_e32 v10, v255, v229
	v_mul_f32_e32 v11, v219, v230
	v_add_f32_e32 v224, v13, v13
	v_add_f32_e32 v225, v14, v14
	v_add_f32_e32 v226, v15, v15
	v_add_f32_e32 v227, v8, v8
	v_add_f32_e32 v228, v9, v9
	v_add_f32_e32 v229, v10, v10
	v_add_f32_e32 v230, v11, v11
	v_fmamk_f32 v17, v224, 0x3c088889, v212
	v_fmamk_f32 v18, v225, 0x3c088889, v212
	v_fmamk_f32 v19, v226, 0x3c088889, v212
	v_fmamk_f32 v20, v227, 0x3c088889, v212
	v_fmamk_f32 v21, v228, 0x3c088889, v212
	v_fmamk_f32 v22, v229, 0x3c088889, v212
	v_fmamk_f32 v23, v230, 0x3c088889, v212
	v_fmaak_f32 v17, v224, v17, 0x3e2aaaab
	v_fmaak_f32 v18, v225, v18, 0x3e2aaaab
	v_fmaak_f32 v19, v226, v19, 0x3e2aaaab
	v_fmaak_f32 v20, v227, v20, 0x3e2aaaab
	v_fmaak_f32 v21, v228, v21, 0x3e2aaaab
	v_fmaak_f32 v22, v229, v22, 0x3e2aaaab
	v_fmaak_f32 v23, v230, v23, 0x3e2aaaab
	v_fma_f32 v17, v224, v17, 0.5
	v_fma_f32 v18, v225, v18, 0.5
	v_fma_f32 v19, v226, v19, 0.5
	v_fma_f32 v20, v227, v20, 0.5
	v_fma_f32 v21, v228, v21, 0.5
	v_fma_f32 v22, v229, v22, 0.5
	v_fma_f32 v23, v230, v23, 0.5
	v_fma_f32 v17, v224, v17, 1.0
	v_fma_f32 v18, v225, v18, 1.0
	v_fma_f32 v19, v226, v19, 1.0
	v_fma_f32 v20, v227, v20, 1.0
	v_fma_f32 v21, v228, v21, 1.0
	v_fma_f32 v22, v229, v22, 1.0
	v_fma_f32 v23, v230, v23, 1.0
	v_mul_f32_e64 v17, v17, -v224
	v_mul_f32_e64 v18, v18, -v225
	v_mul_f32_e64 v19, v19, -v226
	v_mul_f32_e64 v20, v20, -v227
	v_mul_f32_e64 v21, v21, -v228
	v_mul_f32_e64 v22, v22, -v229
	v_mul_f32_e64 v23, v23, -v230
	v_min3_f32 v231, v224, v225, v226
	v_min3_f32 v231, v231, v227, v228
	v_min3_f32 v231, v231, v229, v230
	v_cmp_gt_f32_e32 vcc, s72, v231
	s_cbranch_vccnz .Lp3_rare_7

; __device__ __forceinline__ float fsigmoid(float x) { return __builtin_amdgcn_rcpf(1.0f + __builtin_amdgcn_exp2f(-x * LOG2E)); }
;     __device__ __forceinline__ void operator()(const Acc& acc, const Unit& u, int wr, int wc, int fr, int fq) const {
;     ...
;                     for (int e = 0; e < 4; ++e) { const float rr = fsigmoid(ar[e]), ii = fsigmoid(aiq[e]); const float la = -rr * sp[e], y = 2.0f * la;
;                         float m2 = -y * (1.0f + y * (0.5f + y * (0.16666667f + y * (0.041666668f + y * 0.0083333338f))));
;                         if (__builtin_expect(__any(y < -0.25f), 0)) m2 = (y < -0.25f) ? 1.0f - __builtin_amdgcn_exp2f(y * LOG2E) : m2;
.Lp3_rare_0:
	v_cmp_gt_f32_e32 vcc, s72, v224
	v_mul_f32_e32 v224, 0x3fb8aa3b, v224
	v_exp_f32_e32 v224, v224
	s_nop 0
	v_sub_f32_e32 v224, 1.0, v224
	v_cndmask_b32_e32 v215, v215, v224, vcc
	v_cmp_gt_f32_e32 vcc, s72, v225
	v_mul_f32_e32 v225, 0x3fb8aa3b, v225
	v_exp_f32_e32 v225, v225
	s_nop 0
	v_sub_f32_e32 v225, 1.0, v225
	v_cndmask_b32_e32 v216, v216, v225, vcc
	v_cmp_gt_f32_e32 vcc, s72, v226
	v_mul_f32_e32 v226, 0x3fb8aa3b, v226
	v_exp_f32_e32 v226, v226
	s_nop 0
	v_sub_f32_e32 v226, 1.0, v226
	v_cndmask_b32_e32 v217, v217, v226, vcc
	v_cmp_gt_f32_e32 vcc, s72, v227
	v_mul_f32_e32 v227, 0x3fb8aa3b, v227
	v_exp_f32_e32 v227, v227
	s_nop 0
	v_sub_f32_e32 v227, 1.0, v227
	v_cndmask_b32_e32 v221, v221, v227, vcc
	v_cmp_gt_f32_e32 vcc, s72, v228
	v_mul_f32_e32 v228, 0x3fb8aa3b, v228
	v_exp_f32_e32 v228, v228
	s_nop 0
	v_sub_f32_e32 v228, 1.0, v228
	v_cndmask_b32_e32 v222, v222, v228, vcc
	v_cmp_gt_f32_e32 vcc, s72, v229
	v_mul_f32_e32 v229, 0x3fb8aa3b, v229
	v_exp_f32_e32 v229, v229
	s_nop 0
	v_sub_f32_e32 v229, 1.0, v229
	v_cndmask_b32_e32 v223, v223, v229, vcc
	v_cmp_gt_f32_e32 vcc, s72, v230
	v_mul_f32_e32 v230, 0x3fb8aa3b, v230
	v_exp_f32_e32 v230, v230
	s_nop 0
	v_sub_f32_e32 v230, 1.0, v230
	v_cndmask_b32_e32 v165, v165, v230, vcc
	s_branch .Lp3_ret_0
.Lp3_rare_1:
	v_cmp_gt_f32_e32 vcc, s72, v224
	v_mul_f32_e32 v224, 0x3fb8aa3b, v224
	v_exp_f32_e32 v224, v224
	s_nop 0
	v_sub_f32_e32 v224, 1.0, v224
	v_cndmask_b32_e32 v158, v158, v224, vcc
	v_cmp_gt_f32_e32 vcc, s72, v225
	v_mul_f32_e32 v225, 0x3fb8aa3b, v225
	v_exp_f32_e32 v225, v225
	s_nop 0
	v_sub_f32_e32 v225, 1.0, v225
	v_cndmask_b32_e32 v159, v159, v225, vcc
	v_cmp_gt_f32_e32 vcc, s72, v226
	v_mul_f32_e32 v226, 0x3fb8aa3b, v226
	v_exp_f32_e32 v226, v226
	s_nop 0
	v_sub_f32_e32 v226, 1.0, v226
	v_cndmask_b32_e32 v160, v160, v226, vcc
	v_cmp_gt_f32_e32 vcc, s72, v227
	v_mul_f32_e32 v227, 0x3fb8aa3b, v227
	v_exp_f32_e32 v227, v227
	s_nop 0
	v_sub_f32_e32 v227, 1.0, v227
	v_cndmask_b32_e32 v163, v163, v227, vcc
	v_cmp_gt_f32_e32 vcc, s72, v228
	v_mul_f32_e32 v228, 0x3fb8aa3b, v228
	v_exp_f32_e32 v228, v228
	s_nop 0
	v_sub_f32_e32 v228, 1.0, v228
	v_cndmask_b32_e32 v164, v164, v228, vcc
	v_cmp_gt_f32_e32 vcc, s72, v229
	v_mul_f32_e32 v229, 0x3fb8aa3b, v229
	v_exp_f32_e32 v229, v229
	s_nop 0
	v_sub_f32_e32 v229, 1.0, v229
	v_cndmask_b32_e32 v165, v165, v229, vcc
	v_cmp_gt_f32_e32 vcc, s72, v230
	v_mul_f32_e32 v230, 0x3fb8aa3b, v230
	v_exp_f32_e32 v230, v230
	s_nop 0
	v_sub_f32_e32 v230, 1.0, v230
	v_cndmask_b32_e32 v145, v145, v230, vcc
	s_branch .Lp3_ret_1
.Lp3_rare_2:
	v_cmp_gt_f32_e32 vcc, s72, v224
	v_mul_f32_e32 v224, 0x3fb8aa3b, v224
	v_exp_f32_e32 v224, v224
	s_nop 0
	v_sub_f32_e32 v224, 1.0, v224
	v_cndmask_b32_e32 v133, v133, v224, vcc
	v_cmp_gt_f32_e32 vcc, s72, v225
	v_mul_f32_e32 v225, 0x3fb8aa3b, v225
	v_exp_f32_e32 v225, v225
	s_nop 0
	v_sub_f32_e32 v225, 1.0, v225
	v_cndmask_b32_e32 v134, v134, v225, vcc
	v_cmp_gt_f32_e32 vcc, s72, v226
	v_mul_f32_e32 v226, 0x3fb8aa3b, v226
	v_exp_f32_e32 v226, v226
	s_nop 0
	v_sub_f32_e32 v226, 1.0, v226
	v_cndmask_b32_e32 v135, v135, v226, vcc
	v_cmp_gt_f32_e32 vcc, s72, v227
	v_mul_f32_e32 v227, 0x3fb8aa3b, v227
	v_exp_f32_e32 v227, v227
	s_nop 0
	v_sub_f32_e32 v227, 1.0, v227
	v_cndmask_b32_e32 v142, v142, v227, vcc
	v_cmp_gt_f32_e32 vcc, s72, v228
	v_mul_f32_e32 v228, 0x3fb8aa3b, v228
	v_exp_f32_e32 v228, v228
	s_nop 0
	v_sub_f32_e32 v228, 1.0, v228
	v_cndmask_b32_e32 v143, v143, v228, vcc
	v_cmp_gt_f32_e32 vcc, s72, v229
	v_mul_f32_e32 v229, 0x3fb8aa3b, v229
	v_exp_f32_e32 v229, v229
	s_nop 0
	v_sub_f32_e32 v229, 1.0, v229
	v_cndmask_b32_e32 v144, v144, v229, vcc
	v_cmp_gt_f32_e32 vcc, s72, v230
	v_mul_f32_e32 v230, 0x3fb8aa3b, v230
	v_exp_f32_e32 v230, v230
	s_nop 0
	v_sub_f32_e32 v230, 1.0, v230
	v_cndmask_b32_e32 v125, v125, v230, vcc
	s_branch .Lp3_ret_2
.Lp3_rare_3:
	v_cmp_gt_f32_e32 vcc, s72, v224
	v_mul_f32_e32 v224, 0x3fb8aa3b, v224
	v_exp_f32_e32 v224, v224
	s_nop 0
	v_sub_f32_e32 v224, 1.0, v224
	v_cndmask_b32_e32 v113, v113, v224, vcc
	v_cmp_gt_f32_e32 vcc, s72, v225
	v_mul_f32_e32 v225, 0x3fb8aa3b, v225
	v_exp_f32_e32 v225, v225
	s_nop 0
	v_sub_f32_e32 v225, 1.0, v225
	v_cndmask_b32_e32 v114, v114, v225, vcc
	v_cmp_gt_f32_e32 vcc, s72, v226
	v_mul_f32_e32 v226, 0x3fb8aa3b, v226
	v_exp_f32_e32 v226, v226
	s_nop 0
	v_sub_f32_e32 v226, 1.0, v226
	v_cndmask_b32_e32 v115, v115, v226, vcc
	v_cmp_gt_f32_e32 vcc, s72, v227
	v_mul_f32_e32 v227, 0x3fb8aa3b, v227
	v_exp_f32_e32 v227, v227
	s_nop 0
	v_sub_f32_e32 v227, 1.0, v227
	v_cndmask_b32_e32 v122, v122, v227, vcc
	v_cmp_gt_f32_e32 vcc, s72, v228
	v_mul_f32_e32 v228, 0x3fb8aa3b, v228
	v_exp_f32_e32 v228, v228
	s_nop 0
	v_sub_f32_e32 v228, 1.0, v228
	v_cndmask_b32_e32 v123, v123, v228, vcc
	v_cmp_gt_f32_e32 vcc, s72, v229
	v_mul_f32_e32 v229, 0x3fb8aa3b, v229
	v_exp_f32_e32 v229, v229
	s_nop 0
	v_sub_f32_e32 v229, 1.0, v229
	v_cndmask_b32_e32 v124, v124, v229, vcc
	v_cmp_gt_f32_e32 vcc, s72, v230
	v_mul_f32_e32 v230, 0x3fb8aa3b, v230
	v_exp_f32_e32 v230, v230
	s_nop 0
	v_sub_f32_e32 v230, 1.0, v230
	v_cndmask_b32_e32 v105, v105, v230, vcc
	s_branch .Lp3_ret_3
; __device__ __forceinline__ float fsigmoid(float x) { return __builtin_amdgcn_rcpf(1.0f + __builtin_amdgcn_exp2f(-x * LOG2E)); }
;     __device__ __forceinline__ void operator()(const Acc& acc, const Unit& u, int wr, int wc, int fr, int fq) const {
;     ...
;                     for (int e = 0; e < 4; ++e) { const float rr = fsigmoid(ar[e]), ii = fsigmoid(aiq[e]); const float la = -rr * sp[e], y = 2.0f * la;
;                         float m2 = -y * (1.0f + y * (0.5f + y * (0.16666667f + y * (0.041666668f + y * 0.0083333338f))));
;                         if (__builtin_expect(__any(y < -0.25f), 0)) m2 = (y < -0.25f) ? 1.0f - __builtin_amdgcn_exp2f(y * LOG2E) : m2;
.Lp3_rare_4:
	v_cmp_gt_f32_e32 vcc, s72, v224
	v_mul_f32_e32 v224, 0x3fb8aa3b, v224
	v_exp_f32_e32 v224, v224
	s_nop 0
	v_sub_f32_e32 v224, 1.0, v224
	v_cndmask_b32_e32 v93, v93, v224, vcc
	v_cmp_gt_f32_e32 vcc, s72, v225
	v_mul_f32_e32 v225, 0x3fb8aa3b, v225
	v_exp_f32_e32 v225, v225
	s_nop 0
	v_sub_f32_e32 v225, 1.0, v225
	v_cndmask_b32_e32 v94, v94, v225, vcc
	v_cmp_gt_f32_e32 vcc, s72, v226
	v_mul_f32_e32 v226, 0x3fb8aa3b, v226
	v_exp_f32_e32 v226, v226
	s_nop 0
	v_sub_f32_e32 v226, 1.0, v226
	v_cndmask_b32_e32 v95, v95, v226, vcc
	v_cmp_gt_f32_e32 vcc, s72, v227
	v_mul_f32_e32 v227, 0x3fb8aa3b, v227
	v_exp_f32_e32 v227, v227
	s_nop 0
	v_sub_f32_e32 v227, 1.0, v227
	v_cndmask_b32_e32 v102, v102, v227, vcc
	v_cmp_gt_f32_e32 vcc, s72, v228
	v_mul_f32_e32 v228, 0x3fb8aa3b, v228
	v_exp_f32_e32 v228, v228
	s_nop 0
	v_sub_f32_e32 v228, 1.0, v228
	v_cndmask_b32_e32 v103, v103, v228, vcc
	v_cmp_gt_f32_e32 vcc, s72, v229
	v_mul_f32_e32 v229, 0x3fb8aa3b, v229
	v_exp_f32_e32 v229, v229
	s_nop 0
	v_sub_f32_e32 v229, 1.0, v229
	v_cndmask_b32_e32 v104, v104, v229, vcc
	v_cmp_gt_f32_e32 vcc, s72, v230
	v_mul_f32_e32 v230, 0x3fb8aa3b, v230
	v_exp_f32_e32 v230, v230
	s_nop 0
	v_sub_f32_e32 v230, 1.0, v230
	v_cndmask_b32_e32 v69, v69, v230, vcc
	s_branch .Lp3_ret_4
.Lp3_rare_5:
	v_cmp_gt_f32_e32 vcc, s72, v224
	v_mul_f32_e32 v224, 0x3fb8aa3b, v224
	v_exp_f32_e32 v224, v224
	s_nop 0
	v_sub_f32_e32 v224, 1.0, v224
	v_cndmask_b32_e32 v49, v49, v224, vcc
	v_cmp_gt_f32_e32 vcc, s72, v225
	v_mul_f32_e32 v225, 0x3fb8aa3b, v225
	v_exp_f32_e32 v225, v225
	s_nop 0
	v_sub_f32_e32 v225, 1.0, v225
	v_cndmask_b32_e32 v50, v50, v225, vcc
	v_cmp_gt_f32_e32 vcc, s72, v226
	v_mul_f32_e32 v226, 0x3fb8aa3b, v226
	v_exp_f32_e32 v226, v226
	s_nop 0
	v_sub_f32_e32 v226, 1.0, v226
	v_cndmask_b32_e32 v51, v51, v226, vcc
	v_cmp_gt_f32_e32 vcc, s72, v227
	v_mul_f32_e32 v227, 0x3fb8aa3b, v227
	v_exp_f32_e32 v227, v227
	s_nop 0
	v_sub_f32_e32 v227, 1.0, v227
	v_cndmask_b32_e32 v62, v62, v227, vcc
	v_cmp_gt_f32_e32 vcc, s72, v228
	v_mul_f32_e32 v228, 0x3fb8aa3b, v228
	v_exp_f32_e32 v228, v228
	s_nop 0
	v_sub_f32_e32 v228, 1.0, v228
	v_cndmask_b32_e32 v63, v63, v228, vcc
	v_cmp_gt_f32_e32 vcc, s72, v229
	v_mul_f32_e32 v229, 0x3fb8aa3b, v229
	v_exp_f32_e32 v229, v229
	s_nop 0
	v_sub_f32_e32 v229, 1.0, v229
	v_cndmask_b32_e32 v68, v68, v229, vcc
	v_cmp_gt_f32_e32 vcc, s72, v230
	v_mul_f32_e32 v230, 0x3fb8aa3b, v230
	v_exp_f32_e32 v230, v230
	s_nop 0
	v_sub_f32_e32 v230, 1.0, v230
	v_cndmask_b32_e32 v41, v41, v230, vcc
	s_branch .Lp3_ret_5
.Lp3_rare_6:
	v_cmp_gt_f32_e32 vcc, s72, v224
	v_mul_f32_e32 v224, 0x3fb8aa3b, v224
	v_exp_f32_e32 v224, v224
	s_nop 0
	v_sub_f32_e32 v224, 1.0, v224
	v_cndmask_b32_e32 v33, v33, v224, vcc
	v_cmp_gt_f32_e32 vcc, s72, v225
	v_mul_f32_e32 v225, 0x3fb8aa3b, v225
	v_exp_f32_e32 v225, v225
	s_nop 0
	v_sub_f32_e32 v225, 1.0, v225
	v_cndmask_b32_e32 v34, v34, v225, vcc
	v_cmp_gt_f32_e32 vcc, s72, v226
	v_mul_f32_e32 v226, 0x3fb8aa3b, v226
	v_exp_f32_e32 v226, v226
	s_nop 0
	v_sub_f32_e32 v226, 1.0, v226
	v_cndmask_b32_e32 v35, v35, v226, vcc
	v_cmp_gt_f32_e32 vcc, s72, v227
	v_mul_f32_e32 v227, 0x3fb8aa3b, v227
	v_exp_f32_e32 v227, v227
	s_nop 0
	v_sub_f32_e32 v227, 1.0, v227
	v_cndmask_b32_e32 v38, v38, v227, vcc
	v_cmp_gt_f32_e32 vcc, s72, v228
	v_mul_f32_e32 v228, 0x3fb8aa3b, v228
	v_exp_f32_e32 v228, v228
	s_nop 0
	v_sub_f32_e32 v228, 1.0, v228
	v_cndmask_b32_e32 v39, v39, v228, vcc
	v_cmp_gt_f32_e32 vcc, s72, v229
	v_mul_f32_e32 v229, 0x3fb8aa3b, v229
	v_exp_f32_e32 v229, v229
	s_nop 0
	v_sub_f32_e32 v229, 1.0, v229
	v_cndmask_b32_e32 v40, v40, v229, vcc
	v_cmp_gt_f32_e32 vcc, s72, v230
	v_mul_f32_e32 v230, 0x3fb8aa3b, v230
	v_exp_f32_e32 v230, v230
	s_nop 0
	v_sub_f32_e32 v230, 1.0, v230
	v_cndmask_b32_e32 v25, v25, v230, vcc
	s_branch .Lp3_ret_6
.Lp3_rare_7:
	v_cmp_gt_f32_e32 vcc, s72, v224
	v_mul_f32_e32 v224, 0x3fb8aa3b, v224
	v_exp_f32_e32 v224, v224
	s_nop 0
	v_sub_f32_e32 v224, 1.0, v224
	v_cndmask_b32_e32 v17, v17, v224, vcc
	v_cmp_gt_f32_e32 vcc, s72, v225
	v_mul_f32_e32 v225, 0x3fb8aa3b, v225
	v_exp_f32_e32 v225, v225
	s_nop 0
	v_sub_f32_e32 v225, 1.0, v225
	v_cndmask_b32_e32 v18, v18, v225, vcc
	v_cmp_gt_f32_e32 vcc, s72, v226
	v_mul_f32_e32 v226, 0x3fb8aa3b, v226
	v_exp_f32_e32 v226, v226
	s_nop 0
	v_sub_f32_e32 v226, 1.0, v226
	v_cndmask_b32_e32 v19, v19, v226, vcc
	v_cmp_gt_f32_e32 vcc, s72, v227
	v_mul_f32_e32 v227, 0x3fb8aa3b, v227
	v_exp_f32_e32 v227, v227
	s_nop 0
	v_sub_f32_e32 v227, 1.0, v227
	v_cndmask_b32_e32 v20, v20, v227, vcc
	v_cmp_gt_f32_e32 vcc, s72, v228
	v_mul_f32_e32 v228, 0x3fb8aa3b, v228
	v_exp_f32_e32 v228, v228
	s_nop 0
	v_sub_f32_e32 v228, 1.0, v228
	v_cndmask_b32_e32 v21, v21, v228, vcc
	v_cmp_gt_f32_e32 vcc, s72, v229
	v_mul_f32_e32 v229, 0x3fb8aa3b, v229
	v_exp_f32_e32 v229, v229
	s_nop 0
	v_sub_f32_e32 v229, 1.0, v229
	v_cndmask_b32_e32 v22, v22, v229, vcc
	v_cmp_gt_f32_e32 vcc, s72, v230
	v_mul_f32_e32 v230, 0x3fb8aa3b, v230
	v_exp_f32_e32 v230, v230
	s_nop 0
	v_sub_f32_e32 v230, 1.0, v230
	v_cndmask_b32_e32 v23, v23, v230, vcc
	s_branch .Lp3_ret_7

; #define LAS __attribute__((address_space(3)))
; __device__ __forceinline__ int v_st(int k, int c) { const int kk = k; return ((kk >> 3) * 4 + (c >> 5)) * 512 + ((kk & 7) * 32 + (c & 31)) * 2; }
; __device__ __forceinline__ int v_rd_base(int lane) { return ((lane & 3) << 3) | (((lane >> 2) & 3) << 6) | (((lane >> 4) & 1) << 5) | (((lane >> 5) & 1) << 8); }
; #define ABAR() asm volatile("s_waitcnt lgkmcnt(0)\n\ts_barrier" ::: "memory")
; template <bool FIRST> __device__ __forceinline__ void partialSM(f32x16& p0, f32x16& p1, float& mref, f32x16& negm, float& alpha) {
;   constexpr float THRL = THR * 1.4426950408889634f;
;   float pmax = p0[0];
; #pragma unroll
;   for (int r = 1; r < 16; ++r) pmax = fmaxf(pmax, p0[r]);
; #pragma unroll
;   for (int r = 0; r < 16; ++r) pmax = fmaxf(pmax, p1[r]);
;   { auto rr = __builtin_amdgcn_permlane32_swap(__float_as_uint(pmax), __float_as_uint(pmax), false, false);
;     pmax = fmaxf(__uint_as_float(rr[0]), __uint_as_float(rr[1])); }
;   if (!FIRST && __builtin_expect(__all(pmax <= THRL), 1)) { alpha = 1.f; }
;   else { const float dl = FIRST ? pmax : fmaxf(pmax, 0.f); mref += dl; alpha = FIRST ? 1.f : __builtin_amdgcn_exp2f(-dl);
; #pragma unroll
;     for (int r = 0; r < 16; ++r) { p0[r] -= dl; p1[r] -= dl; }
; __device__ __forceinline__ void attn_unit(const bf16_t* __restrict__ Qb, const bf16_t* __restrict__ KNh, const bf16_t* __restrict__ KRb, const bf16_t* __restrict__ Vh, bf16_t* __restrict__ Ob, char* lds) {
;     ...
;   const int sr = tid >> 3, sc = (tid & 7) * 8, vst = v_st(sr, sc), kst = KSWZ(sr, sc * 2), krst = KSWZ(sr, 128 + (tid & 7) * 8);
;   const lds_cptr vb0 = (lds_cptr)(LAS char*)lds + v_rd_base(lane);
;   struct { bf16x8 vs, ks; s16x4 kr; } sr_[2];
;   const unsigned lo_kv = (unsigned)(sr * 512 + sc), lo_kr = (unsigned)(sr * 32 + (tid & 7) * 4);
;     ...
;   if (__builtin_amdgcn_readfirstlane(tid >> 6) >= 4) __builtin_amdgcn_s_setprio(1);
;   f32x16 pA0, pA1, pB0, pB1; float alA, alB; bf16x8 pa0, pa1, pa2, pa3; constexpr int NT = SEQ / KVBLK;
;   SLOAD(0, 0); SLOAD(1, KVBLK); asm volatile("s_waitcnt vmcnt(0)" ::: "memory"); SWRITE(0, 0); SWRITE(1, 1); SLOAD(0, 2 * KVBLK); ABAR();
;   qkt(pA0, pA1, K_lds, qr, negm, r32, hi); partialSM<true>(pA0, pA1, mref, negm, alA);
;   SWRITE(2, 0); SLOAD(1, 3 * KVBLK); ABAR();
.LBB0_738:
	s_xor_b64 s[34:35], s[30:31], -1
	s_lshr_b32 s91, s33, 3
	s_lshl_b64 s[62:63], s[42:43], 21
	s_add_u32 s44, s14, s62
	s_addc_u32 s45, s15, s63
	s_lshl_b32 s88, s41, 6
	s_lshl_b32 s41, s41, 7
	s_add_u32 s44, s44, s41
	s_addc_u32 s45, s45, 0
	s_lshl_b64 s[64:65], s[42:43], 17
	s_add_u32 s42, s24, s64
	v_readlane_b32 s43, v252, 36
	s_addc_u32 s43, s43, s65
	s_add_u32 s46, s25, s62
	s_addc_u32 s47, s97, s63
	s_add_u32 s46, s46, s41
	s_addc_u32 s47, s47, 0
	v_mov_b32_e32 v169, v153
	v_lshl_add_u64 v[52:53], s[46:47], 0, v[168:169]
	s_mov_b32 s89, 0x10000
	v_add_co_u32_e32 v8, vcc, s89, v52
	v_lshl_add_u64 v[50:51], s[44:45], 0, v[168:169]
	s_nop 0
	v_addc_co_u32_e32 v9, vcc, 0, v53, vcc
	v_add_co_u32_e32 v12, vcc, s89, v50
	global_load_dwordx4 v[0:3], v168, s[46:47]
	s_nop 0
	v_addc_co_u32_e32 v13, vcc, 0, v51, vcc
	global_load_dwordx4 v[4:7], v168, s[44:45]
	global_load_dwordx2 v[16:17], v170, s[42:43]
	s_nop 0
	global_load_dwordx4 v[8:11], v[8:9], off
	s_nop 0
	global_load_dwordx4 v[12:15], v[12:13], off
	v_mov_b32_e32 v171, v153
	v_lshl_add_u64 v[48:49], s[42:43], 0, v[170:171]
	v_add_co_u32_e32 v18, vcc, s70, v48
	v_add_u32_e32 v26, s85, v201
	s_nop 0
	v_addc_co_u32_e32 v19, vcc, 0, v49, vcc
	global_load_dwordx2 v[20:21], v[18:19], off offset:-4096
	v_add_co_u32_e32 v22, vcc, s67, v50
	s_waitcnt vmcnt(0)
	v_add_u32_e32 v27, s85, v202
	s_nop 0
	v_addc_co_u32_e32 v23, vcc, 0, v51, vcc
	v_add_co_u32_e32 v24, vcc, s67, v52
	v_add_u32_e32 v28, s82, v201
	s_nop 0
	v_addc_co_u32_e32 v25, vcc, 0, v53, vcc
	v_add_u32_e32 v29, s82, v202
	global_load_dwordx4 v[136:139], v[24:25], off
	global_load_dwordx4 v[140:143], v[22:23], off
	global_load_dwordx2 v[172:173], v[18:19], off
	v_add_u32_e32 v30, s85, v206
	v_add_co_u32_e32 v62, vcc, s84, v52
	v_add_u32_e32 v64, s85, v211
	s_nop 0
	v_addc_co_u32_e32 v63, vcc, 0, v53, vcc
	s_mov_b32 s41, s40
	s_mov_b32 s42, s40
	s_mov_b32 s43, s40
	s_mov_b32 s44, s40
	s_mov_b32 s45, s40
	s_mov_b32 s46, s40
	s_mov_b32 s47, s40
	s_mov_b32 s48, s40
	s_mov_b32 s49, s40
	s_mov_b32 s50, s40
	s_mov_b32 s51, s40
	s_mov_b32 s52, s40
	s_mov_b32 s53, s40
	s_mov_b32 s54, s40
	s_mov_b32 s55, s40
	s_mov_b32 s90, 1
	v_mov_b32_e32 v177, s65
	v_or_b32_e32 v176, s64, v154
	v_mov_b32_e32 v152, 0
	v_mov_b32_e32 v163, 1.0
	s_waitcnt vmcnt(7)
	ds_write_b128 v26, v[4:7]
	s_waitcnt vmcnt(6)
	ds_write_b64 v27, v[16:17]
	ds_write_b128 v204, v[0:3]
	s_waitcnt vmcnt(5)
	ds_write_b128 v204, v[8:11] offset:16384
	s_waitcnt vmcnt(4)
	ds_write_b128 v28, v[12:15]
	s_waitcnt vmcnt(3)
	ds_write_b64 v29, v[20:21]
	s_waitcnt lgkmcnt(0)
	s_barrier
	ds_read_b128 v[0:3], v30
	ds_read_b128 v[4:7], v30 offset:8192
	s_waitcnt lgkmcnt(1)
	v_mfma_f32_32x32x16_bf16 v[32:47], v[0:3], v[132:135], 0
	v_add_u32_e32 v8, s85, v207
	s_waitcnt lgkmcnt(0)
	v_mfma_f32_32x32x16_bf16 v[16:31], v[4:7], v[132:135], 0
	ds_read_b128 v[0:3], v8
	ds_read_b128 v[4:7], v8 offset:8192
	v_add_u32_e32 v8, s85, v208
	s_waitcnt lgkmcnt(1)
	v_mfma_f32_32x32x16_bf16 v[32:47], v[0:3], v[128:131], v[32:47]
	s_waitcnt lgkmcnt(0)
	v_mfma_f32_32x32x16_bf16 v[16:31], v[4:7], v[128:131], v[16:31]
	ds_read_b128 v[0:3], v8
	ds_read_b128 v[4:7], v8 offset:8192
	v_add_u32_e32 v8, s85, v209
	ds_read_b128 v[58:61], v64
	s_waitcnt lgkmcnt(2)
	v_mfma_f32_32x32x16_bf16 v[32:47], v[0:3], v[124:127], v[32:47]
	ds_read_b128 v[0:3], v8
	s_waitcnt lgkmcnt(2)
	v_mfma_f32_32x32x16_bf16 v[16:31], v[4:7], v[124:127], v[16:31]
	ds_read_b128 v[4:7], v8 offset:8192
	v_add_u32_e32 v8, s85, v210
	ds_read_b128 v[54:57], v8 offset:8192
	s_waitcnt lgkmcnt(2)
	v_mfma_f32_32x32x16_bf16 v[32:47], v[0:3], v[120:123], v[32:47]
	ds_read_b128 v[0:3], v8
	s_waitcnt lgkmcnt(2)
	v_mfma_f32_32x32x16_bf16 v[16:31], v[4:7], v[120:123], v[16:31]
	s_waitcnt lgkmcnt(1)
	v_mfma_f32_32x32x16_bf16 v[16:31], v[54:57], v[116:119], v[16:31]
	v_add_co_u32_e32 v54, vcc, s84, v50
	s_nop 1
	v_addc_co_u32_e32 v55, vcc, 0, v51, vcc
	v_add_co_u32_e32 v48, vcc, s80, v48
	ds_read_b128 v[50:53], v64 offset:8192
	s_nop 0
	v_addc_co_u32_e32 v49, vcc, 0, v49, vcc
	global_load_dwordx4 v[144:147], v[62:63], off
	global_load_dwordx4 v[148:151], v[54:55], off
	global_load_dwordx2 v[174:175], v[48:49], off
	s_waitcnt lgkmcnt(1)
	v_mfma_f32_32x32x16_bf16 v[32:47], v[0:3], v[116:119], v[32:47]
	v_mov_b64_e32 v[0:1], s[40:41]
	v_mov_b64_e32 v[2:3], s[42:43]
	v_mov_b64_e32 v[4:5], s[44:45]
	v_mov_b64_e32 v[6:7], s[46:47]
	v_mov_b64_e32 v[8:9], s[48:49]
	v_mov_b64_e32 v[10:11], s[50:51]
	v_mov_b64_e32 v[12:13], s[52:53]
	v_mfma_f32_32x32x16_bf16 v[32:47], v[58:61], v[112:115], v[32:47]
	v_mov_b64_e32 v[14:15], s[54:55]
	s_and_b32 s41, s91, 7
	s_waitcnt vmcnt(5)
	ds_write_b128 v204, v[136:139] offset:32768
	s_lshl_b32 s41, s41, 7
	s_or_b32 s62, s62, s41
	v_lshl_add_u64 v[178:179], s[62:63], 0, v[158:159]
	s_add_u32 s98, s22, s62
	s_addc_u32 s99, s23, s63
	s_add_u32 s98, s98, 0x40000
	s_addc_u32 s99, s99, 0
	s_add_u32 s100, s22, s64
	s_addc_u32 s101, s23, s65
	s_add_u32 s100, s100, 0x4000
	s_addc_u32 s101, s101, 0
	v_add_u32_e32 v240, 0x2a800000, v158
	v_add_u32_e32 v241, 0x26800000, v158
	v_add_u32_e32 v242, 0x2e800000, v154
	s_nop 4
	v_max_f32_e32 v48, v33, v33
	v_max_f32_e32 v49, v32, v32
	s_waitcnt lgkmcnt(1)
	v_mfma_f32_32x32x16_bf16 v[16:31], v[50:53], v[112:115], v[16:31]
	v_max_f32_e32 v48, v49, v48
	v_max3_f32 v48, v48, v34, v35
	v_max3_f32 v48, v48, v36, v37
	v_max3_f32 v48, v48, v38, v39
	v_max3_f32 v48, v48, v40, v41
	v_max3_f32 v48, v48, v42, v43
	v_max3_f32 v48, v48, v44, v45
	v_max3_f32 v48, v48, v46, v47
	s_nop 3
	v_max3_f32 v48, v48, v16, v17
	v_max3_f32 v48, v48, v18, v19
	v_max3_f32 v48, v48, v20, v21
	v_max3_f32 v48, v48, v22, v23
	v_max3_f32 v48, v48, v24, v25
	v_max3_f32 v48, v48, v26, v27
	v_max3_f32 v48, v48, v28, v29
	v_max3_f32 v48, v48, v30, v31
	v_mov_b32_e32 v49, v48
	s_nop 1
	v_permlane32_swap_b32_e32 v48, v49
	v_max_f32_e32 v49, v49, v49
	v_max_f32_e32 v48, v48, v48
	v_max_f32_e32 v48, v48, v49
	v_sub_f32_e32 v64, v16, v48
	v_add_u32_e32 v16, s83, v201
	v_sub_f32_e32 v49, v32, v48
	v_sub_f32_e32 v33, v33, v48
	v_sub_f32_e32 v34, v34, v48
	v_sub_f32_e32 v35, v35, v48
	v_sub_f32_e32 v36, v36, v48
	v_sub_f32_e32 v37, v37, v48
	v_sub_f32_e32 v38, v38, v48
	v_sub_f32_e32 v39, v39, v48
	v_sub_f32_e32 v40, v40, v48
	v_sub_f32_e32 v41, v41, v48
	v_sub_f32_e32 v42, v42, v48
	v_sub_f32_e32 v43, v43, v48
	v_sub_f32_e32 v44, v44, v48
	v_sub_f32_e32 v45, v45, v48
	v_sub_f32_e32 v46, v46, v48
	v_sub_f32_e32 v47, v47, v48
	s_waitcnt vmcnt(4)
	ds_write_b128 v16, v[140:143]
	v_add_u32_e32 v16, s83, v202
	v_exp_f32_e32 v194, v49
	v_exp_f32_e32 v216, v33
	v_exp_f32_e32 v192, v34
	v_exp_f32_e32 v195, v35
	v_exp_f32_e32 v190, v36
	v_exp_f32_e32 v193, v37
	v_exp_f32_e32 v189, v38
	v_exp_f32_e32 v191, v39
	v_exp_f32_e32 v186, v40
	v_exp_f32_e32 v188, v41
	v_exp_f32_e32 v185, v42
	v_exp_f32_e32 v187, v43
	v_exp_f32_e32 v181, v44
	v_exp_f32_e32 v183, v45
	v_exp_f32_e32 v180, v46
	v_exp_f32_e32 v182, v47
	s_waitcnt vmcnt(3)
	ds_write_b64 v16, v[172:173]
	v_add_f32_e32 v161, 0, v48
	s_waitcnt lgkmcnt(0)
	s_barrier
; #define SBAR() __builtin_amdgcn_sched_barrier(0)
; #define PK4(P, BASE, OUT) do { u32x4 w = {cvt_pk_bf16(P[BASE + 0], P[BASE + 1]), cvt_pk_bf16(P[BASE + 2], P[BASE + 3]), cvt_pk_bf16(P[BASE + 4], P[BASE + 5]), cvt_pk_bf16(P[BASE + 6], P[BASE + 7])}; \
;     OUT = *reinterpret_cast<bf16x8*>(&w); } while (0)
; #define SLOAD(i, k0) do { const bf16_t* vt_ = Vh + (size_t)(k0) * 512; const bf16_t* kt_ = KNh + (size_t)(k0) * 512; const bf16_t* rt_ = KRb + (size_t)(k0) * 32; \
;     sr_[i].vs = *reinterpret_cast<const bf16x8*>(vt_ + lo_kv); sr_[i].ks = *reinterpret_cast<const bf16x8*>(kt_ + lo_kv); sr_[i].kr = *reinterpret_cast<const s16x4*>(rt_ + lo_kr); } while (0)
; #define SWRITE(slot, i) do { *(bf16x8*)(V_lds + (slot) * SHM_V + vst) = sr_[i].vs; *(bf16x8*)(K_lds + (slot) * SHM_K + kst) = sr_[i].ks; *(s16x4*)(K_lds + (slot) * SHM_K + krst) = sr_[i].kr; } while (0)
; __device__ __forceinline__ void finishSM(f32x16& p0, f32x16& p1, float alpha, float& l_reg, bf16x8& pa0, bf16x8& pa1, bf16x8& pa2, bf16x8& pa3) {
; #pragma unroll
;   for (int r = 0; r < 16; ++r) p1[r] = __builtin_amdgcn_exp2f(p1[r]);
;   float ps = 0;
; #pragma unroll
;   for (int r = 0; r < 16; ++r) ps += p0[r];
; #pragma unroll
;   for (int r = 0; r < 16; ++r) ps += p1[r];
;   { auto rr = __builtin_amdgcn_permlane32_swap(__float_as_uint(ps), __float_as_uint(ps), false, false);
;     ps = __uint_as_float(rr[0]) + __uint_as_float(rr[1]); }
;   l_reg = l_reg * alpha + ps;
;     ...
;   PK4(p0, 0, pa0); PK4(p0, 8, pa1); PK4(p1, 0, pa2); PK4(p1, 8, pa3);
; __device__ __forceinline__ void attn_unit(const bf16_t* __restrict__ Qb, const bf16_t* __restrict__ KNh, const bf16_t* __restrict__ KRb, const bf16_t* __restrict__ Vh, bf16_t* __restrict__ Ob, char* lds) {
;     ...
;   for (int j = 1; j + 1 < NT; j += 2) {
;     SBAR(); qkt(pB0, pB1, K_lds + (j & 3) * SHM_K, qr, negm, r32, hi);
;     finishSM(pA0, pA1, alA, l_reg, pa0, pa1, pa2, pa3); SBAR();
;     if (j + 2 < NT) { SWRITE((j + 2) & 3, 1); } if (j + 3 < NT) { SLOAD(0, (j + 3) * KVBLK); } SBAR();
	v_sub_f32_e32 v79, v31, v48
	v_sub_f32_e32 v78, v30, v48
	v_sub_f32_e32 v77, v29, v48
	v_sub_f32_e32 v76, v28, v48
	v_sub_f32_e32 v75, v27, v48
	v_sub_f32_e32 v74, v26, v48
	v_sub_f32_e32 v73, v25, v48
	v_sub_f32_e32 v72, v24, v48
	v_sub_f32_e32 v71, v23, v48
	v_sub_f32_e32 v70, v22, v48
	v_sub_f32_e32 v69, v21, v48
	v_sub_f32_e32 v68, v20, v48
	v_sub_f32_e32 v67, v19, v48
	v_sub_f32_e32 v66, v18, v48
	v_sub_f32_e32 v65, v17, v48
	v_xor_b32_e32 v32, 0x80000000, v161
	v_mov_b64_e32 v[30:31], v[14:15]
	v_mov_b64_e32 v[28:29], v[12:13]
	v_mov_b64_e32 v[26:27], v[10:11]
	v_mov_b64_e32 v[24:25], v[8:9]
	v_mov_b64_e32 v[22:23], v[6:7]
	v_mov_b64_e32 v[20:21], v[4:5]
	v_mov_b64_e32 v[18:19], v[2:3]
	v_mov_b64_e32 v[16:17], v[0:1]
	v_mov_b32_e32 v33, v32
	v_mov_b32_e32 v34, v32
	v_mov_b32_e32 v35, v32
	v_mov_b32_e32 v36, v32
	v_mov_b32_e32 v37, v32
	v_mov_b32_e32 v38, v32
	v_mov_b32_e32 v39, v32
	v_mov_b32_e32 v40, v32
	v_mov_b32_e32 v41, v32
	v_mov_b32_e32 v42, v32
	v_mov_b32_e32 v43, v32
	v_mov_b32_e32 v44, v32
	v_mov_b32_e32 v45, v32
	v_mov_b32_e32 v46, v32
	v_mov_b32_e32 v47, v32
.LBB0_739:
	s_add_i32 s41, s89, 0xffff4000
	s_and_b32 s41, s41, 0xc000
	s_add_i32 s42, s85, s41
	v_add_u32_e32 v52, s42, v206
	ds_read_b128 v[48:51], v52
	ds_read_b128 v[52:55], v52 offset:8192
	v_add_u32_e32 v56, s42, v207
	v_add_u32_e32 v60, s42, v208
	v_add_u32_e32 v165, s42, v209
	s_waitcnt lgkmcnt(1)
	v_mfma_f32_32x32x16_bf16 v[96:111], v[48:51], v[132:135], v[32:47]
	ds_read_b128 v[48:51], v56
	ds_read_b128 v[56:59], v56 offset:8192
	v_add_u32_e32 v167, s42, v210
	v_exp_f32_e32 v64, v64
	v_exp_f32_e32 v65, v65
	v_exp_f32_e32 v66, v66
	v_exp_f32_e32 v67, v67
	v_exp_f32_e32 v68, v68
	s_waitcnt lgkmcnt(2)
	v_mfma_f32_32x32x16_bf16 v[80:95], v[52:55], v[132:135], v[32:47]
	ds_read_b128 v[52:55], v60
	ds_read_b128 v[60:63], v60 offset:8192
	ds_read_b128 v[220:223], v165
	ds_read_b128 v[224:227], v165 offset:8192
	ds_read_b128 v[228:231], v167
	ds_read_b128 v[232:235], v167 offset:8192
	v_exp_f32_e32 v69, v69
	v_exp_f32_e32 v70, v70
	v_exp_f32_e32 v71, v71
	v_add_u32_e32 v169, s42, v211
	v_exp_f32_e32 v72, v72
	v_exp_f32_e32 v73, v73
	s_waitcnt lgkmcnt(7)
	v_mfma_f32_32x32x16_bf16 v[96:111], v[48:51], v[128:131], v[96:111]
	ds_read_b128 v[48:51], v169
	ds_read_b128 v[236:239], v169 offset:8192
	v_exp_f32_e32 v74, v74
	v_exp_f32_e32 v75, v75
	v_exp_f32_e32 v76, v76
	v_exp_f32_e32 v77, v77
	v_exp_f32_e32 v78, v78
	v_exp_f32_e32 v79, v79
	s_waitcnt lgkmcnt(8)
	v_mfma_f32_32x32x16_bf16 v[80:95], v[56:59], v[128:131], v[80:95]
	s_waitcnt lgkmcnt(7)
	v_mfma_f32_32x32x16_bf16 v[96:111], v[52:55], v[124:127], v[96:111]
	v_add_f32_e32 v52, 0, v194
	v_add_f32_e32 v52, v216, v52
	v_add_f32_e32 v52, v192, v52
	v_add_f32_e32 v52, v195, v52
	v_add_f32_e32 v52, v190, v52
	v_add_f32_e32 v52, v193, v52
	v_add_f32_e32 v52, v189, v52
	s_waitcnt lgkmcnt(6)
	v_mfma_f32_32x32x16_bf16 v[80:95], v[60:63], v[124:127], v[80:95]
	v_add_f32_e32 v52, v191, v52
	v_add_f32_e32 v52, v186, v52
	v_add_f32_e32 v52, v188, v52
	v_add_f32_e32 v52, v185, v52
	v_add_f32_e32 v52, v187, v52
	v_add_f32_e32 v52, v181, v52
	v_add_f32_e32 v52, v183, v52
	s_waitcnt lgkmcnt(5)
	v_mfma_f32_32x32x16_bf16 v[96:111], v[220:223], v[120:123], v[96:111]
	v_add_f32_e32 v52, v180, v52
	v_add_f32_e32 v52, v182, v52
	v_add_f32_e32 v52, v64, v52
	v_add_f32_e32 v52, v65, v52
	v_add_f32_e32 v52, v66, v52
	v_add_f32_e32 v52, v67, v52
	v_add_f32_e32 v52, v68, v52
	s_waitcnt lgkmcnt(4)
	v_mfma_f32_32x32x16_bf16 v[80:95], v[224:227], v[120:123], v[80:95]
	v_add_f32_e32 v52, v69, v52
	v_add_f32_e32 v52, v70, v52
	v_add_f32_e32 v52, v71, v52
	v_add_f32_e32 v52, v72, v52
	v_add_f32_e32 v52, v73, v52
	v_add_f32_e32 v52, v74, v52
	v_add_f32_e32 v52, v75, v52
	s_waitcnt lgkmcnt(3)
	v_mfma_f32_32x32x16_bf16 v[96:111], v[228:231], v[116:119], v[96:111]
	v_add_f32_e32 v52, v76, v52
	v_add_f32_e32 v52, v77, v52
	v_add_f32_e32 v52, v78, v52
	v_add_f32_e32 v165, v79, v52
	v_mov_b32_e32 v167, v165
	s_nop 1
	v_permlane32_swap_b32_e32 v165, v167
	s_waitcnt lgkmcnt(2)
	v_mfma_f32_32x32x16_bf16 v[80:95], v[232:235], v[116:119], v[80:95]
	v_cvt_pk_bf16_f32 v60, v194, v216
	v_cvt_pk_bf16_f32 v61, v192, v195
	v_cvt_pk_bf16_f32 v62, v190, v193
	v_cvt_pk_bf16_f32 v63, v189, v191
	v_cvt_pk_bf16_f32 v56, v186, v188
	v_cvt_pk_bf16_f32 v57, v185, v187
	v_cvt_pk_bf16_f32 v58, v181, v183
	s_waitcnt lgkmcnt(1)
	v_mfma_f32_32x32x16_bf16 v[96:111], v[48:51], v[112:115], v[96:111]
	v_cvt_pk_bf16_f32 v59, v180, v182
	v_cvt_pk_bf16_f32 v52, v64, v65
	v_cvt_pk_bf16_f32 v53, v66, v67
	v_cvt_pk_bf16_f32 v54, v68, v69
	v_cvt_pk_bf16_f32 v55, v70, v71
	v_cvt_pk_bf16_f32 v48, v72, v73
	v_cvt_pk_bf16_f32 v49, v74, v75
	s_waitcnt lgkmcnt(0)
	v_mfma_f32_32x32x16_bf16 v[80:95], v[236:239], v[112:115], v[80:95]
	v_cvt_pk_bf16_f32 v50, v76, v77
	v_cvt_pk_bf16_f32 v51, v78, v79
	s_add_i32 s42, s89, 0xffffc000
	s_and_b32 s42, s42, 0xc000
	s_add_i32 s43, s85, s42
	s_cmp_lt_u32 s90, 29
	s_cselect_b64 s[44:45], -1, 0
	s_cmp_gt_u32 s90, 28
	v_add_u32_e32 v64, s43, v202
	v_add_u32_e32 v65, s43, v201
	v_add_u32_e32 v66, s42, v204
	s_cselect_b64 s[42:43], -1, 0
	s_and_b64 vcc, exec, s[42:43]
	s_waitcnt vmcnt(2)
	ds_write_b128 v66, v[144:147]
	s_waitcnt vmcnt(1)
	ds_write_b128 v65, v[148:151]
	s_waitcnt vmcnt(0)
	ds_write_b64 v64, v[174:175]
	s_cbranch_vccnz .LBB0_741
	global_load_dwordx4 v[136:139], v240, s[98:99]
	global_load_dwordx4 v[140:143], v241, s[98:99]
	global_load_dwordx2 v[172:173], v242, s[100:101]
	s_add_u32 s98, s98, 0x10000
	s_addc_u32 s99, s99, 0
	s_add_u32 s100, s100, 0x1000
	s_addc_u32 s101, s101, 0
; __device__ __forceinline__ s16x4 vtr(lds_cptr p) { return __builtin_bit_cast(s16x4, __builtin_amdgcn_ds_read_tr16_b64_v4i16((LAS v4i16_t*)p)); }
; template <bool FIRST> __device__ __forceinline__ void partialSM(f32x16& p0, f32x16& p1, float& mref, f32x16& negm, float& alpha) {
;   constexpr float THRL = THR * 1.4426950408889634f;
;   float pmax = p0[0];
; #pragma unroll
;   for (int r = 1; r < 16; ++r) pmax = fmaxf(pmax, p0[r]);
; #pragma unroll
;   for (int r = 0; r < 16; ++r) pmax = fmaxf(pmax, p1[r]);
;   { auto rr = __builtin_amdgcn_permlane32_swap(__float_as_uint(pmax), __float_as_uint(pmax), false, false);
;     pmax = fmaxf(__uint_as_float(rr[0]), __uint_as_float(rr[1])); }
;   if (!FIRST && __builtin_expect(__all(pmax <= THRL), 1)) { alpha = 1.f; }
; template <int D0> __device__ __forceinline__ void pv_one(f32x16& od, lds_cptr vp, bf16x8 pa0, bf16x8 pa1, bf16x8 pa2, bf16x8 pa3) {
;   const s16x4 l0 = vtr(vp + v_rd_off(D0, 0, 0)), h0 = vtr(vp + v_rd_off(D0, 0, 1)), l1 = vtr(vp + v_rd_off(D0, 1, 0)), h1 = vtr(vp + v_rd_off(D0, 1, 1));
;   const s16x4 l2 = vtr(vp + v_rd_off(D0, 2, 0)), h2 = vtr(vp + v_rd_off(D0, 2, 1)), l3 = vtr(vp + v_rd_off(D0, 3, 0)), h3 = vtr(vp + v_rd_off(D0, 3, 1));
;     ...
;   od = __builtin_amdgcn_mfma_f32_32x32x16_bf16(pa0, PK(l0, h0), od, 0, 0, 0);
;   od = __builtin_amdgcn_mfma_f32_32x32x16_bf16(pa1, PK(l1, h1), od, 0, 0, 0);
;   od = __builtin_amdgcn_mfma_f32_32x32x16_bf16(pa2, PK(l2, h2), od, 0, 0, 0);
;   od = __builtin_amdgcn_mfma_f32_32x32x16_bf16(pa3, PK(l3, h3), od, 0, 0, 0);
;     ...
; }
; __device__ __forceinline__ void pv_d0(f32x16* o, lds_cptr vp, bf16x8 pa0, bf16x8 pa1, bf16x8 pa2, bf16x8 pa3) {
;   pv_one<0>(o[0], vp, pa0, pa1, pa2, pa3); pv_one<1>(o[1], vp, pa0, pa1, pa2, pa3);
.LBB0_741:
	s_and_b32 s48, s89, 0xc000
	v_add_u32_e32 v169, s48, v203
	ds_read_b64_tr_b16 v[64:65], v169
	ds_read_b64_tr_b16 v[66:67], v169 offset:2048
	ds_read_b64_tr_b16 v[70:71], v169 offset:2560
	ds_read_b64_tr_b16 v[68:69], v169 offset:512
	s_waitcnt lgkmcnt(2)
	v_mfma_f32_32x32x16_bf16 v[0:15], v[60:63], v[64:67], v[0:15]
	ds_read_b64_tr_b16 v[64:65], v169 offset:4096
	ds_read_b64_tr_b16 v[66:67], v169 offset:6144
	ds_read_b64_tr_b16 v[74:75], v169 offset:6656
	ds_read_b64_tr_b16 v[72:73], v169 offset:4608
	s_waitcnt lgkmcnt(2)
	v_mfma_f32_32x32x16_bf16 v[0:15], v[56:59], v[64:67], v[0:15]
	ds_read_b64_tr_b16 v[64:65], v169 offset:8192
	ds_read_b64_tr_b16 v[66:67], v169 offset:10240
	ds_read_b64_tr_b16 v[78:79], v169 offset:10752
	ds_read_b64_tr_b16 v[76:77], v169 offset:8704
	v_mfma_f32_32x32x16_bf16 v[16:31], v[60:63], v[68:71], v[16:31]
	s_waitcnt lgkmcnt(2)
	v_mfma_f32_32x32x16_bf16 v[0:15], v[52:55], v[64:67], v[0:15]
	ds_read_b64_tr_b16 v[64:65], v169 offset:12288
	ds_read_b64_tr_b16 v[66:67], v169 offset:14336
	ds_read_b64_tr_b16 v[186:187], v169 offset:14848
	ds_read_b64_tr_b16 v[184:185], v169 offset:12800
	v_mfma_f32_32x32x16_bf16 v[16:31], v[56:59], v[72:75], v[16:31]
	s_waitcnt lgkmcnt(2)
	v_mfma_f32_32x32x16_bf16 v[0:15], v[48:51], v[64:67], v[0:15]
	v_max_f32_e32 v64, v97, v97
	v_max_f32_e32 v65, v96, v96
	v_max_f32_e32 v64, v65, v64
	v_max3_f32 v64, v64, v98, v99
	v_max3_f32 v60, v64, v100, v101
	v_max3_f32 v60, v60, v102, v103
	v_max3_f32 v60, v60, v104, v105
	v_max3_f32 v60, v60, v106, v107
	v_max3_f32 v60, v60, v108, v109
	v_mfma_f32_32x32x16_bf16 v[16:31], v[52:55], v[76:79], v[16:31]
	v_max3_f32 v60, v60, v110, v111
	v_max3_f32 v60, v60, v80, v81
	v_max3_f32 v56, v60, v82, v83
	v_max3_f32 v56, v56, v84, v85
	v_max3_f32 v56, v56, v86, v87
	v_max3_f32 v56, v56, v88, v89
	v_max3_f32 v56, v56, v90, v91
	v_max3_f32 v56, v56, v92, v93
	s_waitcnt lgkmcnt(0)
	v_mfma_f32_32x32x16_bf16 v[16:31], v[48:51], v[184:187], v[16:31]
	v_max3_f32 v56, v56, v94, v95
	v_mov_b32_e32 v52, v56
	s_nop 1
	v_permlane32_swap_b32_e32 v56, v52
	v_max_f32_e32 v52, v52, v52
	v_max_f32_e32 v53, v56, v56
	v_max_f32_e32 v52, v53, v52
	v_cmp_ge_f32_e32 vcc, s86, v52
	s_cmp_eq_u64 vcc, exec
	s_cbranch_scc0 .LBB0_757
	v_mov_b32_e32 v169, 1.0
	v_cmp_gt_f32_e32 vcc, 1.0, v169
	s_cbranch_vccz .LBB0_746

; #define SBAR() __builtin_amdgcn_sched_barrier(0)
; #define PK4(P, BASE, OUT) do { u32x4 w = {cvt_pk_bf16(P[BASE + 0], P[BASE + 1]), cvt_pk_bf16(P[BASE + 2], P[BASE + 3]), cvt_pk_bf16(P[BASE + 4], P[BASE + 5]), cvt_pk_bf16(P[BASE + 6], P[BASE + 7])}; \
;     OUT = *reinterpret_cast<bf16x8*>(&w); } while (0)
; #define SLOAD(i, k0) do { const bf16_t* vt_ = Vh + (size_t)(k0) * 512; const bf16_t* kt_ = KNh + (size_t)(k0) * 512; const bf16_t* rt_ = KRb + (size_t)(k0) * 32; \
;     sr_[i].vs = *reinterpret_cast<const bf16x8*>(vt_ + lo_kv); sr_[i].ks = *reinterpret_cast<const bf16x8*>(kt_ + lo_kv); sr_[i].kr = *reinterpret_cast<const s16x4*>(rt_ + lo_kr); } while (0)
; #define SWRITE(slot, i) do { *(bf16x8*)(V_lds + (slot) * SHM_V + vst) = sr_[i].vs; *(bf16x8*)(K_lds + (slot) * SHM_K + kst) = sr_[i].ks; *(s16x4*)(K_lds + (slot) * SHM_K + krst) = sr_[i].kr; } while (0)
; __device__ __forceinline__ void finishSM(f32x16& p0, f32x16& p1, float alpha, float& l_reg, bf16x8& pa0, bf16x8& pa1, bf16x8& pa2, bf16x8& pa3) {
; #pragma unroll
;   for (int r = 0; r < 16; ++r) p1[r] = __builtin_amdgcn_exp2f(p1[r]);
;   float ps = 0;
; #pragma unroll
;   for (int r = 0; r < 16; ++r) ps += p0[r];
; #pragma unroll
;   for (int r = 0; r < 16; ++r) ps += p1[r];
;   { auto rr = __builtin_amdgcn_permlane32_swap(__float_as_uint(ps), __float_as_uint(ps), false, false);
;     ps = __uint_as_float(rr[0]) + __uint_as_float(rr[1]); }
;   l_reg = l_reg * alpha + ps;
;     ...
;   PK4(p0, 0, pa0); PK4(p0, 8, pa1); PK4(p1, 0, pa2); PK4(p1, 8, pa3);
; __device__ __forceinline__ void attn_unit(const bf16_t* __restrict__ Qb, const bf16_t* __restrict__ KNh, const bf16_t* __restrict__ KRb, const bf16_t* __restrict__ Vh, bf16_t* __restrict__ Ob, char* lds) {
;     ...
;     SBAR(); qkt(pA0, pA1, K_lds + ((j + 1) & 3) * SHM_K, qr, negm, r32, hi);
;     finishSM(pB0, pB1, alB, l_reg, pa0, pa1, pa2, pa3); SBAR();
;     if (j + 3 < NT) { SWRITE((j + 3) & 3, 0); } if (j + 4 < NT) { SLOAD(1, (j + 4) * KVBLK); } SBAR();
.LBB0_746:
	s_waitcnt lgkmcnt(0)
	s_barrier
	v_exp_f32_e32 v192, v96
	v_exp_f32_e32 v193, v97
	v_exp_f32_e32 v194, v98
	v_exp_f32_e32 v195, v99
	v_exp_f32_e32 v216, v100
	v_exp_f32_e32 v217, v101
	v_exp_f32_e32 v219, v102
	v_exp_f32_e32 v220, v103
	v_exp_f32_e32 v221, v104
	v_exp_f32_e32 v222, v105
	v_exp_f32_e32 v223, v106
	v_exp_f32_e32 v224, v107
	v_exp_f32_e32 v225, v108
	v_exp_f32_e32 v226, v109
	v_exp_f32_e32 v227, v110
	v_exp_f32_e32 v228, v111
	s_add_i32 s46, s89, 0xffff8000
	s_and_b32 s46, s46, 0xc000
	s_add_i32 s46, s46, 0
	s_add_i32 s46, s46, 0x10000
	v_add_u32_e32 v68, s46, v206
	ds_read_b128 v[64:67], v68
	ds_read_b128 v[184:187], v68 offset:8192
	v_add_u32_e32 v171, s46, v207
	v_exp_f32_e32 v80, v80
	v_exp_f32_e32 v81, v81
	s_waitcnt lgkmcnt(1)
	v_mfma_f32_32x32x16_bf16 v[96:111], v[64:67], v[132:135], v[32:47]
	v_exp_f32_e32 v82, v82
	v_exp_f32_e32 v83, v83
	v_exp_f32_e32 v87, v87
	v_exp_f32_e32 v229, v92
	v_exp_f32_e32 v230, v93
	v_exp_f32_e32 v231, v94
	v_exp_f32_e32 v232, v95
	s_waitcnt lgkmcnt(0)
	v_mfma_f32_32x32x16_bf16 v[64:79], v[184:187], v[132:135], v[32:47]
	ds_read_b128 v[184:187], v171
	ds_read_b128 v[188:191], v171 offset:8192
	v_add_u32_e32 v171, s46, v208
	s_waitcnt lgkmcnt(1)
	v_mfma_f32_32x32x16_bf16 v[96:111], v[184:187], v[128:131], v[96:111]
	s_waitcnt lgkmcnt(0)
	v_mfma_f32_32x32x16_bf16 v[64:79], v[188:191], v[128:131], v[64:79]
	ds_read_b128 v[184:187], v171
	ds_read_b128 v[188:191], v171 offset:8192
	v_add_u32_e32 v171, s46, v209
	s_waitcnt lgkmcnt(1)
	v_mfma_f32_32x32x16_bf16 v[96:111], v[184:187], v[124:127], v[96:111]
	s_waitcnt lgkmcnt(0)
	v_mfma_f32_32x32x16_bf16 v[64:79], v[188:191], v[124:127], v[64:79]
	ds_read_b128 v[184:187], v171
	ds_read_b128 v[188:191], v171 offset:8192
	v_add_u32_e32 v171, s46, v210
	s_waitcnt lgkmcnt(1)
	v_mfma_f32_32x32x16_bf16 v[96:111], v[184:187], v[120:123], v[96:111]
	s_waitcnt lgkmcnt(0)
	v_mfma_f32_32x32x16_bf16 v[64:79], v[188:191], v[120:123], v[64:79]
	ds_read_b128 v[184:187], v171
	ds_read_b128 v[188:191], v171 offset:8192
	v_add_u32_e32 v171, s46, v211
	s_waitcnt lgkmcnt(1)
	v_mfma_f32_32x32x16_bf16 v[96:111], v[184:187], v[116:119], v[96:111]
	s_waitcnt lgkmcnt(0)
	v_mfma_f32_32x32x16_bf16 v[64:79], v[188:191], v[116:119], v[64:79]
	ds_read_b128 v[184:187], v171
	ds_read_b128 v[188:191], v171 offset:8192
	v_cvt_pk_bf16_f32 v92, v192, v193
	v_cvt_pk_bf16_f32 v93, v194, v195
	v_cvt_pk_bf16_f32 v94, v216, v217
	v_cvt_pk_bf16_f32 v95, v219, v220
	s_waitcnt lgkmcnt(1)
	v_mfma_f32_32x32x16_bf16 v[96:111], v[184:187], v[112:115], v[96:111]
	v_exp_f32_e32 v185, v84
	v_add_f32_e32 v84, 0, v192
	v_add_f32_e32 v84, v193, v84
	v_add_f32_e32 v84, v194, v84
	v_add_f32_e32 v84, v195, v84
	v_add_f32_e32 v84, v216, v84
	v_add_f32_e32 v84, v217, v84
	v_add_f32_e32 v84, v219, v84
	v_add_f32_e32 v84, v220, v84
	v_add_f32_e32 v84, v221, v84
	v_add_f32_e32 v84, v222, v84
	v_add_f32_e32 v84, v223, v84
	v_add_f32_e32 v84, v224, v84
	v_add_f32_e32 v84, v225, v84
	v_add_f32_e32 v84, v226, v84
	v_add_f32_e32 v84, v227, v84
	v_add_f32_e32 v84, v228, v84
	v_add_f32_e32 v84, v80, v84
	v_exp_f32_e32 v186, v85
	v_add_f32_e32 v84, v81, v84
	v_exp_f32_e32 v187, v86
	v_add_f32_e32 v84, v82, v84
	v_add_f32_e32 v84, v83, v84
	s_waitcnt lgkmcnt(0)
	v_mfma_f32_32x32x16_bf16 v[64:79], v[188:191], v[112:115], v[64:79]
	v_exp_f32_e32 v188, v88
	v_add_f32_e32 v84, v185, v84
	v_exp_f32_e32 v189, v89
	v_add_f32_e32 v84, v186, v84
	v_exp_f32_e32 v190, v90
	v_add_f32_e32 v84, v187, v84
	v_exp_f32_e32 v191, v91
	v_add_f32_e32 v84, v87, v84
	v_add_f32_e32 v84, v188, v84
	v_add_f32_e32 v84, v189, v84
	v_add_f32_e32 v84, v190, v84
	v_add_f32_e32 v84, v191, v84
	v_add_f32_e32 v84, v229, v84
	v_add_f32_e32 v84, v230, v84
	v_add_f32_e32 v84, v231, v84
	v_add_f32_e32 v171, v232, v84
	v_mov_b32_e32 v184, v171
	s_nop 1
	v_permlane32_swap_b32_e32 v171, v184
	v_cvt_pk_bf16_f32 v88, v221, v222
	v_cvt_pk_bf16_f32 v89, v223, v224
	v_cvt_pk_bf16_f32 v90, v225, v226
	v_cvt_pk_bf16_f32 v91, v227, v228
	v_cvt_pk_bf16_f32 v84, v80, v81
	v_cvt_pk_bf16_f32 v85, v82, v83
	v_cvt_pk_bf16_f32 v86, v185, v186
	v_cvt_pk_bf16_f32 v87, v187, v87
	v_cvt_pk_bf16_f32 v80, v188, v189
	v_cvt_pk_bf16_f32 v81, v190, v191
	v_cvt_pk_bf16_f32 v82, v229, v230
	v_cvt_pk_bf16_f32 v83, v231, v232
	s_andn2_b64 vcc, exec, s[44:45]
	s_cbranch_vccnz .LBB0_748
	s_add_i32 s44, s48, 0
	v_add_u32_e32 v185, s48, v204
	s_add_i32 s44, s44, 0x10000
	v_add_u32_e32 v186, s44, v201
	v_add_u32_e32 v187, s44, v202
	s_waitcnt vmcnt(2)
	ds_write_b128 v185, v[136:139]
	s_waitcnt vmcnt(1)
	ds_write_b128 v186, v[140:143]
	s_waitcnt vmcnt(0)
	ds_write_b64 v187, v[172:173]
.LBB0_748:
	s_cmp_gt_u32 s90, 27
	s_cbranch_scc1 .LBB0_750
	global_load_dwordx4 v[144:147], v240, s[98:99]
	global_load_dwordx4 v[148:151], v241, s[98:99]
	global_load_dwordx2 v[174:175], v242, s[100:101]
	s_add_u32 s98, s98, 0x10000
	s_addc_u32 s99, s99, 0
	s_add_u32 s100, s100, 0x1000
	s_addc_u32 s101, s101, 0

; #define SBAR() __builtin_amdgcn_sched_barrier(0)
; #define ABAR() asm volatile("s_waitcnt lgkmcnt(0)\n\ts_barrier" ::: "memory")
; #define SLOAD(i, k0) do { const bf16_t* vt_ = Vh + (size_t)(k0) * 512; const bf16_t* kt_ = KNh + (size_t)(k0) * 512; const bf16_t* rt_ = KRb + (size_t)(k0) * 32; \
;     sr_[i].vs = *reinterpret_cast<const bf16x8*>(vt_ + lo_kv); sr_[i].ks = *reinterpret_cast<const bf16x8*>(kt_ + lo_kv); sr_[i].kr = *reinterpret_cast<const s16x4*>(rt_ + lo_kr); } while (0)
; #define SWRITE(slot, i) do { *(bf16x8*)(V_lds + (slot) * SHM_V + vst) = sr_[i].vs; *(bf16x8*)(K_lds + (slot) * SHM_K + kst) = sr_[i].ks; *(s16x4*)(K_lds + (slot) * SHM_K + krst) = sr_[i].kr; } while (0)
; #define RESC(a) do { if (__any((a) < 1.f)) { if (hi == 0) al_l[r32] = (a); asm volatile("s_waitcnt lgkmcnt(0)" ::: "memory"); \
;     _Pragma("unroll") for (int d = 0; d < 2; ++d) _Pragma("unroll") for (int r = 0; r < 16; ++r) o[d][r] *= al_l[crow(r, hi)]; } } while (0)
; __device__ __forceinline__ void attn_unit(const bf16_t* __restrict__ Qb, const bf16_t* __restrict__ KNh, const bf16_t* __restrict__ KRb, const bf16_t* __restrict__ Vh, bf16_t* __restrict__ Ob, char* lds) {
;     ...
;   for (int j = 1; j + 1 < NT; j += 2) {
;     SBAR(); qkt(pB0, pB1, K_lds + (j & 3) * SHM_K, qr, negm, r32, hi);
;     finishSM(pA0, pA1, alA, l_reg, pa0, pa1, pa2, pa3); SBAR();
;     if (j + 2 < NT) { SWRITE((j + 2) & 3, 1); } if (j + 3 < NT) { SLOAD(0, (j + 3) * KVBLK); } SBAR();
;     pv_d0(o, vb0 + ((j - 1) & 3) * SHM_V, pa0, pa1, pa2, pa3); partialSM<false>(pB0, pB1, mref, negm, alB);
;     RESC(alB); ABAR();
;     SBAR(); qkt(pA0, pA1, K_lds + ((j + 1) & 3) * SHM_K, qr, negm, r32, hi);
;     finishSM(pB0, pB1, alB, l_reg, pa0, pa1, pa2, pa3); SBAR();
;     if (j + 3 < NT) { SWRITE((j + 3) & 3, 0); } if (j + 4 < NT) { SLOAD(1, (j + 4) * KVBLK); } SBAR();
;     pv_d0(o, vb0 + (j & 3) * SHM_V, pa0, pa1, pa2, pa3); partialSM<false>(pA0, pA1, mref, negm, alA);
;     RESC(alA); ABAR();
.LBB0_755:
	v_exp_f32_e32 v194, v96
	v_exp_f32_e32 v216, v97
	v_exp_f32_e32 v192, v98
	v_exp_f32_e32 v195, v99
	v_exp_f32_e32 v190, v100
	v_exp_f32_e32 v193, v101
	v_exp_f32_e32 v189, v102
	v_exp_f32_e32 v191, v103
	v_exp_f32_e32 v186, v104
	v_exp_f32_e32 v188, v105
	v_exp_f32_e32 v185, v106
	v_exp_f32_e32 v187, v107
	v_exp_f32_e32 v181, v108
	v_exp_f32_e32 v183, v109
	v_exp_f32_e32 v180, v110
	v_exp_f32_e32 v182, v111
	v_add_f32_e32 v80, v165, v167
	s_waitcnt lgkmcnt(0)
	s_barrier
	v_fmac_f32_e32 v80, v163, v152
	v_add_f32_e32 v152, v171, v184
	v_fmac_f32_e32 v152, v80, v169
	s_add_i32 s90, s90, 2
	s_add_i32 s89, s89, 0x8000
	s_and_b64 vcc, exec, s[42:43]
	s_cbranch_vccnz .LBB0_780
	v_mov_b32_e32 v163, v84
	s_branch .LBB0_739

; #define SBAR() __builtin_amdgcn_sched_barrier(0)
; #define RESC(a) do { if (__any((a) < 1.f)) { if (hi == 0) al_l[r32] = (a); asm volatile("s_waitcnt lgkmcnt(0)" ::: "memory"); \
;     _Pragma("unroll") for (int d = 0; d < 2; ++d) _Pragma("unroll") for (int r = 0; r < 16; ++r) o[d][r] *= al_l[crow(r, hi)]; } } while (0)
; __device__ __forceinline__ void attn_unit(const bf16_t* __restrict__ Qb, const bf16_t* __restrict__ KNh, const bf16_t* __restrict__ KRb, const bf16_t* __restrict__ Vh, bf16_t* __restrict__ Ob, char* lds) {
;     ...
;   SBAR(); qkt(pB0, pB1, K_lds + ((NT - 1) & 3) * SHM_K, qr, negm, r32, hi);
;   finishSM(pA0, pA1, alA, l_reg, pa0, pa1, pa2, pa3); SBAR();
;   pv_d0(o, vb0 + ((NT - 2) & 3) * SHM_V, pa0, pa1, pa2, pa3); partialSM<false>(pB0, pB1, mref, negm, alB);
;   RESC(alB);
;   finishSM(pB0, pB1, alB, l_reg, pa0, pa1, pa2, pa3); SBAR();
;   pv_d0(o, vb0 + ((NT - 1) & 3) * SHM_V, pa0, pa1, pa2, pa3);
.LBB0_780:
	v_mov_b64_e32 v[48:49], v[32:33]
	v_mov_b64_e32 v[50:51], v[34:35]
	v_mov_b64_e32 v[52:53], v[36:37]
	v_mov_b64_e32 v[54:55], v[38:39]
	v_mov_b64_e32 v[56:57], v[40:41]
	v_mov_b64_e32 v[58:59], v[42:43]
	v_mov_b64_e32 v[60:61], v[44:45]
	v_mov_b64_e32 v[62:63], v[46:47]
	s_add_i32 s41, 0, 0x1c000
	v_add_u32_e32 v32, s41, v206
	ds_read_b128 v[80:83], v32
	ds_read_b128 v[86:89], v32 offset:8192
	v_add_u32_e32 v85, s41, v207
	v_add_u32_e32 v98, s41, v208
	v_add_u32_e32 v102, s41, v209
	s_waitcnt lgkmcnt(1)
	v_mfma_f32_32x32x16_bf16 v[32:47], v[80:83], v[132:135], v[48:63]
	ds_read_b128 v[80:83], v85
	ds_read_b128 v[90:93], v85 offset:8192
	ds_read_b128 v[94:97], v98
	ds_read_b128 v[98:101], v98 offset:8192
	v_add_u32_e32 v85, s41, v210
	v_exp_f32_e32 v110, v69
	v_exp_f32_e32 v111, v70
	s_waitcnt lgkmcnt(4)
	v_mfma_f32_32x32x16_bf16 v[48:63], v[86:89], v[132:135], v[48:63]
	ds_read_b128 v[86:89], v102
	ds_read_b128 v[102:105], v102 offset:8192
	ds_read_b128 v[106:109], v85
	ds_read_b128 v[132:135], v85 offset:8192
	v_add_u32_e32 v85, s41, v211
	s_waitcnt vmcnt(2)
	ds_read_b128 v[136:139], v85
	s_waitcnt vmcnt(1)
	ds_read_b128 v[140:143], v85 offset:8192
	v_exp_f32_e32 v85, v68
	s_waitcnt lgkmcnt(9)
	v_mfma_f32_32x32x16_bf16 v[32:47], v[80:83], v[128:131], v[32:47]
	v_exp_f32_e32 v80, v64
	v_add_f32_e32 v64, 0, v194
	v_add_f32_e32 v64, v216, v64
	v_add_f32_e32 v64, v192, v64
	v_add_f32_e32 v64, v195, v64
	v_add_f32_e32 v64, v190, v64
	v_add_f32_e32 v64, v193, v64
	s_waitcnt lgkmcnt(8)
	v_mfma_f32_32x32x16_bf16 v[48:63], v[90:93], v[128:131], v[48:63]
	v_add_f32_e32 v64, v189, v64
	v_add_f32_e32 v64, v191, v64
	v_add_f32_e32 v64, v186, v64
	v_add_f32_e32 v64, v188, v64
	v_add_f32_e32 v64, v185, v64
	v_add_f32_e32 v64, v187, v64
	v_add_f32_e32 v64, v181, v64
	s_waitcnt lgkmcnt(7)
	v_mfma_f32_32x32x16_bf16 v[32:47], v[94:97], v[124:127], v[32:47]
	v_exp_f32_e32 v81, v65
	v_add_f32_e32 v64, v183, v64
	v_exp_f32_e32 v82, v66
	v_add_f32_e32 v64, v180, v64
	v_exp_f32_e32 v83, v67
	v_add_f32_e32 v64, v182, v64
	v_add_f32_e32 v64, v80, v64
	s_waitcnt lgkmcnt(6)
	v_mfma_f32_32x32x16_bf16 v[48:63], v[98:101], v[124:127], v[48:63]
	v_add_f32_e32 v64, v81, v64
	v_add_f32_e32 v64, v82, v64
	v_exp_f32_e32 v90, v71
	v_add_f32_e32 v64, v83, v64
	v_exp_f32_e32 v91, v72
	v_add_f32_e32 v64, v85, v64
	v_exp_f32_e32 v92, v73
	s_waitcnt lgkmcnt(5)
	v_mfma_f32_32x32x16_bf16 v[32:47], v[86:89], v[120:123], v[32:47]
	v_add_f32_e32 v64, v110, v64
	v_exp_f32_e32 v93, v74
	v_add_f32_e32 v64, v111, v64
	v_exp_f32_e32 v128, v75
	v_add_f32_e32 v64, v90, v64
	v_exp_f32_e32 v129, v76
	v_add_f32_e32 v64, v91, v64
	s_waitcnt lgkmcnt(4)
	v_mfma_f32_32x32x16_bf16 v[48:63], v[102:105], v[120:123], v[48:63]
	v_exp_f32_e32 v130, v77
	v_add_f32_e32 v64, v92, v64
	v_exp_f32_e32 v94, v78
	v_add_f32_e32 v64, v93, v64
	v_exp_f32_e32 v95, v79
	v_add_f32_e32 v64, v128, v64
	v_add_f32_e32 v64, v129, v64
	s_waitcnt lgkmcnt(3)
	v_mfma_f32_32x32x16_bf16 v[32:47], v[106:109], v[116:119], v[32:47]
	v_add_f32_e32 v64, v130, v64
	v_add_f32_e32 v64, v94, v64
	v_add_f32_e32 v64, v95, v64
	v_mov_b32_e32 v65, v64
	s_nop 1
	v_permlane32_swap_b32_e32 v64, v65
	v_cvt_pk_bf16_f32 v66, v194, v216
	s_waitcnt lgkmcnt(2)
	v_mfma_f32_32x32x16_bf16 v[48:63], v[132:135], v[116:119], v[48:63]
	v_cvt_pk_bf16_f32 v67, v192, v195
	v_cvt_pk_bf16_f32 v68, v190, v193
	v_cvt_pk_bf16_f32 v69, v189, v191
	v_cvt_pk_bf16_f32 v70, v186, v188
	v_cvt_pk_bf16_f32 v71, v185, v187
	v_cvt_pk_bf16_f32 v72, v181, v183
	v_cvt_pk_bf16_f32 v73, v180, v182
	s_waitcnt lgkmcnt(1)
	v_mfma_f32_32x32x16_bf16 v[32:47], v[136:139], v[112:115], v[32:47]
	v_cvt_pk_bf16_f32 v74, v80, v81
	v_cvt_pk_bf16_f32 v75, v82, v83
	v_cvt_pk_bf16_f32 v76, v85, v110
	v_cvt_pk_bf16_f32 v77, v111, v90
	v_cvt_pk_bf16_f32 v78, v91, v92
	v_cvt_pk_bf16_f32 v79, v93, v128
	v_cvt_pk_bf16_f32 v80, v129, v130
	s_waitcnt lgkmcnt(0)
	v_mfma_f32_32x32x16_bf16 v[48:63], v[140:143], v[112:115], v[48:63]
	v_cvt_pk_bf16_f32 v81, v94, v95
	ds_read_b64_tr_b16 v[86:87], v203 offset:32768
	ds_read_b64_tr_b16 v[88:89], v203 offset:34816
	ds_read_b64_tr_b16 v[92:93], v203 offset:35328
	ds_read_b64_tr_b16 v[90:91], v203 offset:33280
	s_nop 5
	v_max_f32_e32 v82, v33, v33
	v_max_f32_e32 v83, v32, v32
	s_waitcnt lgkmcnt(2)
	v_mfma_f32_32x32x16_bf16 v[0:15], v[66:69], v[86:89], v[0:15]
	ds_read_b64_tr_b16 v[86:87], v203 offset:36864
	ds_read_b64_tr_b16 v[88:89], v203 offset:38912
	ds_read_b64_tr_b16 v[96:97], v203 offset:39424
	ds_read_b64_tr_b16 v[94:95], v203 offset:37376
	v_max_f32_e32 v82, v83, v82
	v_max3_f32 v82, v82, v34, v35
	v_max3_f32 v82, v82, v36, v37
	s_waitcnt lgkmcnt(4)
	v_mfma_f32_32x32x16_bf16 v[16:31], v[66:69], v[90:93], v[16:31]
	v_max3_f32 v66, v82, v38, v39
	v_max3_f32 v66, v66, v40, v41
	v_max3_f32 v66, v66, v42, v43
	v_max3_f32 v66, v66, v44, v45
	v_max3_f32 v66, v66, v46, v47
	v_max3_f32 v66, v66, v48, v49
	v_max3_f32 v66, v66, v50, v51
	s_waitcnt lgkmcnt(2)
	v_mfma_f32_32x32x16_bf16 v[0:15], v[70:73], v[86:89], v[0:15]
	ds_read_b64_tr_b16 v[86:87], v203 offset:40960
	ds_read_b64_tr_b16 v[88:89], v203 offset:43008
	ds_read_b64_tr_b16 v[100:101], v203 offset:43520
	ds_read_b64_tr_b16 v[98:99], v203 offset:41472
	v_max3_f32 v66, v66, v52, v53
	v_max3_f32 v66, v66, v54, v55
	v_max3_f32 v66, v66, v56, v57
	v_max3_f32 v66, v66, v58, v59
	v_max3_f32 v66, v66, v60, v61
	v_max3_f32 v66, v66, v62, v63
	s_waitcnt lgkmcnt(4)
	v_mfma_f32_32x32x16_bf16 v[16:31], v[70:73], v[94:97], v[16:31]
	v_mov_b32_e32 v67, v66
	s_nop 1
	v_permlane32_swap_b32_e32 v66, v67
	v_max_f32_e32 v67, v67, v67
	v_max_f32_e32 v66, v66, v66
	v_max_f32_e32 v67, v66, v67
	v_cmp_ge_f32_e32 vcc, s86, v67
	s_waitcnt lgkmcnt(2)
	v_mfma_f32_32x32x16_bf16 v[0:15], v[74:77], v[86:89], v[0:15]
	ds_read_b64_tr_b16 v[86:87], v203 offset:45056
	ds_read_b64_tr_b16 v[88:89], v203 offset:47104
	ds_read_b64_tr_b16 v[104:105], v203 offset:47616
	ds_read_b64_tr_b16 v[102:103], v203 offset:45568
	s_cmp_eq_u64 vcc, exec
	v_mov_b32_e32 v66, 1.0
	s_waitcnt lgkmcnt(4)
	v_mfma_f32_32x32x16_bf16 v[16:31], v[74:77], v[98:101], v[16:31]
	s_waitcnt lgkmcnt(2)
	v_mfma_f32_32x32x16_bf16 v[0:15], v[78:81], v[86:89], v[0:15]
	s_waitcnt lgkmcnt(0)
	v_mfma_f32_32x32x16_bf16 v[16:31], v[78:81], v[102:105], v[16:31]
	s_cbranch_scc0 .LBB0_787
	v_cmp_gt_f32_e32 vcc, 1.0, v66
	s_cbranch_vccz .LBB0_785

; __global__ void __launch_bounds__(512, 2) mega_fwd(Args args) {
	.amdhsa_kernel _Z8mega_fwd4Args
		.amdhsa_group_segment_fixed_size 0
		.amdhsa_private_segment_fixed_size 0
		.amdhsa_kernarg_size 456
		.amdhsa_user_sgpr_count 2
		.amdhsa_user_sgpr_dispatch_ptr 0
		.amdhsa_user_sgpr_queue_ptr 0
		.amdhsa_user_sgpr_kernarg_segment_ptr 1
		.amdhsa_user_sgpr_dispatch_id 0
		.amdhsa_user_sgpr_kernarg_preload_length 0
		.amdhsa_user_sgpr_kernarg_preload_offset 0
		.amdhsa_user_sgpr_private_segment_size 0
		.amdhsa_uses_dynamic_stack 0
		.amdhsa_enable_private_segment 0
		.amdhsa_system_sgpr_workgroup_id_x 1
		.amdhsa_system_sgpr_workgroup_id_y 0
		.amdhsa_system_sgpr_workgroup_id_z 0
		.amdhsa_system_sgpr_workgroup_info 0
		.amdhsa_system_vgpr_workitem_id 2
		.amdhsa_next_free_vgpr 256
		.amdhsa_next_free_sgpr 102
		.amdhsa_accum_offset 256
		.amdhsa_reserve_vcc 1
		.amdhsa_float_round_mode_32 0
		.amdhsa_float_round_mode_16_64 0
		.amdhsa_float_denorm_mode_32 3
		.amdhsa_float_denorm_mode_16_64 3
		.amdhsa_dx10_clamp 1
		.amdhsa_ieee_mode 1
		.amdhsa_fp16_overflow 0
		.amdhsa_tg_split 0
		.amdhsa_exception_fp_ieee_invalid_op 0
		.amdhsa_exception_fp_denorm_src 0
		.amdhsa_exception_fp_ieee_div_zero 0
		.amdhsa_exception_fp_ieee_overflow 0
		.amdhsa_exception_fp_ieee_underflow 0
		.amdhsa_exception_fp_ieee_inexact 0
		.amdhsa_exception_int_div_zero 0
	.end_amdhsa_kernel

; __global__ void __launch_bounds__(512, 2) mega_fwd(Args args) {
amdhsa.kernels:
  - .agpr_count:     0
    .args:
      - .offset:         0
        .size:           200
        .value_kind:     by_value
      - .offset:         200
        .size:           4
        .value_kind:     hidden_block_count_x
      - .offset:         204
        .size:           4
        .value_kind:     hidden_block_count_y
      - .offset:         208
        .size:           4
        .value_kind:     hidden_block_count_z
      - .offset:         212
        .size:           2
        .value_kind:     hidden_group_size_x
      - .offset:         214
        .size:           2
        .value_kind:     hidden_group_size_y
      - .offset:         216
        .size:           2
        .value_kind:     hidden_group_size_z
      - .offset:         218
        .size:           2
        .value_kind:     hidden_remainder_x
      - .offset:         220
        .size:           2
        .value_kind:     hidden_remainder_y
      - .offset:         222
        .size:           2
        .value_kind:     hidden_remainder_z
      - .offset:         240
        .size:           8
        .value_kind:     hidden_global_offset_x
      - .offset:         248
        .size:           8
        .value_kind:     hidden_global_offset_y
      - .offset:         256
        .size:           8
        .value_kind:     hidden_global_offset_z
      - .offset:         264
        .size:           2
        .value_kind:     hidden_grid_dims
      - .offset:         288
        .size:           8
        .value_kind:     hidden_multigrid_sync_arg
      - .offset:         320
        .size:           4
        .value_kind:     hidden_dynamic_lds_size
    .group_segment_fixed_size: 0
    .kernarg_segment_align: 8
    .kernarg_segment_size: 456
    .language:       OpenCL C
    .language_version:
      - 2
      - 0
    .max_flat_workgroup_size: 512
    .name:           _Z8mega_fwd4Args
    .private_segment_fixed_size: 0
    .sgpr_count:     108
    .sgpr_spill_count: 41
    .symbol:         _Z8mega_fwd4Args.kd
    .uniform_work_group_size: 1
    .uses_dynamic_stack: false
    .vgpr_count:     256
    .vgpr_spill_count: 0
    .wavefront_size: 64
